# nt (streaming) hint on the once-read f32 weight loads of the weight-conversion and adaLN GEMV loops
# speedup vs baseline: 1.0173x; 1.0173x over previous
.LBB0_281:
	s_cmpk_gt_i32 s5, 0x3ff
	s_mov_b64 s[0:1], -1
	s_cbranch_scc0 .LBB0_283
	s_and_b32 s0, s4, 0x7fffff00
	s_add_i32 s64, s0, 0xffffe000
	s_and_b32 s0, s3, 0x7c0
	v_mov_b32_e32 v33, v224
	s_lshl_b32 s1, s0, 2
	v_lshlrev_b32_e32 v0, 4, v33
	v_ashrrev_i32_e32 v34, 4, v33
	v_add_u32_e32 v4, 0x200, v33
	s_add_u32 s14, s55, s1
	v_and_b32_e32 v192, 0xf0, v0
	v_add_u32_e32 v0, s64, v34
	v_ashrrev_i32_e32 v36, 4, v4
	v_add_u32_e32 v8, 0x400, v33
	s_addc_u32 s15, s58, 0
	s_waitcnt lgkmcnt(0)
	v_ashrrev_i32_e32 v1, 31, v0
	v_add_u32_e32 v4, s64, v36
	v_ashrrev_i32_e32 v37, 4, v8
	v_add_u32_e32 v12, 0x600, v33
	v_lshl_add_u64 v[28:29], s[14:15], 0, v[192:193]
	v_lshlrev_b64 v[0:1], 13, v[0:1]
	v_ashrrev_i32_e32 v5, 31, v4
	v_add_u32_e32 v8, s64, v37
	v_ashrrev_i32_e32 v38, 4, v12
	v_add_u32_e32 v16, 0x800, v33
	v_lshl_add_u64 v[0:1], v[28:29], 0, v[0:1]
	v_lshlrev_b64 v[4:5], 13, v[4:5]
	v_ashrrev_i32_e32 v9, 31, v8
	v_add_u32_e32 v12, s64, v38
	v_ashrrev_i32_e32 v39, 4, v16
	v_add_u32_e32 v20, 0xa00, v33
	global_load_dwordx4 v[0:3], v[0:1], off nt
	v_lshl_add_u64 v[4:5], v[28:29], 0, v[4:5]
	v_lshlrev_b64 v[8:9], 13, v[8:9]
	v_ashrrev_i32_e32 v13, 31, v12
	v_add_u32_e32 v16, s64, v39
	v_ashrrev_i32_e32 v40, 4, v20
	v_add_u32_e32 v24, 0xc00, v33
	global_load_dwordx4 v[4:7], v[4:5], off nt
	v_lshl_add_u64 v[8:9], v[28:29], 0, v[8:9]
	v_lshlrev_b64 v[12:13], 13, v[12:13]
	v_ashrrev_i32_e32 v17, 31, v16
	v_add_u32_e32 v20, s64, v40
	v_ashrrev_i32_e32 v41, 4, v24
	v_add_u32_e32 v30, 0xe00, v33
	global_load_dwordx4 v[8:11], v[8:9], off nt
	v_lshl_add_u64 v[12:13], v[28:29], 0, v[12:13]
	v_lshlrev_b64 v[16:17], 13, v[16:17]
	v_ashrrev_i32_e32 v21, 31, v20
	v_add_u32_e32 v24, s64, v41
	v_ashrrev_i32_e32 v42, 4, v30
	global_load_dwordx4 v[12:15], v[12:13], off nt
	v_lshl_add_u64 v[16:17], v[28:29], 0, v[16:17]
	v_lshlrev_b64 v[20:21], 13, v[20:21]
	v_ashrrev_i32_e32 v25, 31, v24
	v_add_u32_e32 v30, s64, v42
	global_load_dwordx4 v[16:19], v[16:17], off nt
	v_lshl_add_u64 v[20:21], v[28:29], 0, v[20:21]
	v_lshlrev_b64 v[24:25], 13, v[24:25]
	v_ashrrev_i32_e32 v31, 31, v30
	global_load_dwordx4 v[20:23], v[20:21], off nt
	v_lshl_add_u64 v[24:25], v[28:29], 0, v[24:25]
	v_lshlrev_b64 v[30:31], 13, v[30:31]
	global_load_dwordx4 v[24:27], v[24:25], off nt
	v_lshl_add_u64 v[28:29], v[28:29], 0, v[30:31]
	global_load_dwordx4 v[28:31], v[28:29], off nt
	v_add_u32_e32 v32, 0, v192
	v_mad_u64_u32 v[34:35], s[14:15], v34, s97, v[32:33]
	s_waitcnt vmcnt(0)
	ds_write2_b32 v34, v0, v1 offset1:1
	ds_write2_b32 v34, v2, v3 offset0:2 offset1:3
	v_mad_u64_u32 v[0:1], s[14:15], v36, s97, v[32:33]
	ds_write2_b32 v0, v4, v5 offset1:1
	ds_write2_b32 v0, v6, v7 offset0:2 offset1:3
	v_mad_u64_u32 v[0:1], s[14:15], v37, s97, v[32:33]
	ds_write2_b32 v0, v8, v9 offset1:1
	ds_write2_b32 v0, v10, v11 offset0:2 offset1:3
	v_mad_u64_u32 v[0:1], s[14:15], v38, s97, v[32:33]
	ds_write2_b32 v0, v12, v13 offset1:1
	ds_write2_b32 v0, v14, v15 offset0:2 offset1:3
	v_mad_u64_u32 v[0:1], s[14:15], v39, s97, v[32:33]
	ds_write2_b32 v0, v16, v17 offset1:1
	ds_write2_b32 v0, v18, v19 offset0:2 offset1:3
	v_mad_u64_u32 v[0:1], s[14:15], v40, s97, v[32:33]
	ds_write2_b32 v0, v20, v21 offset1:1
	ds_write2_b32 v0, v22, v23 offset0:2 offset1:3
	v_mad_u64_u32 v[0:1], s[14:15], v41, s97, v[32:33]
	ds_write2_b32 v0, v24, v25 offset1:1
	ds_write2_b32 v0, v26, v27 offset0:2 offset1:3
	v_mad_u64_u32 v[0:1], s[14:15], v42, s97, v[32:33]
	v_ashrrev_i32_e32 v2, 3, v33
	ds_write2_b32 v0, v28, v29 offset1:1
	ds_write2_b32 v0, v30, v31 offset0:2 offset1:3
	v_add_u32_e32 v0, s0, v2
	v_lshlrev_b32_e32 v3, 3, v33
	v_ashrrev_i32_e32 v1, 31, v0
	v_and_b32_e32 v3, 56, v3
	v_lshlrev_b32_e32 v2, 2, v2
	v_mul_u32_u24_e32 v4, 0x104, v3
	v_lshlrev_b64 v[0:1], 14, v[0:1]
	v_add3_u32 v32, 0, v2, v4
	v_lshl_add_u64 v[0:1], s[62:63], 0, v[0:1]
	v_lshl_add_u64 v[0:1], s[64:65], 1, v[0:1]
	v_lshlrev_b32_e32 v192, 1, v3
	v_add_u32_e32 v8, 0x400, v32
	s_waitcnt lgkmcnt(0)
	s_barrier
	v_lshl_add_u64 v[4:5], v[0:1], 0, v[192:193]
	ds_read2_b32 v[0:1], v32 offset1:65
	ds_read2_b32 v[2:3], v32 offset0:130 offset1:195
	ds_read2_b32 v[6:7], v8 offset0:4 offset1:69
	ds_read2_b32 v[8:9], v8 offset0:134 offset1:199
	v_add_u32_e32 v10, 0x4000, v32
	v_add_u32_e32 v12, 0x4200, v32
	v_add_u32_e32 v14, 0x4400, v32
	v_add_u32_e32 v16, 0x4600, v32
	v_add_u32_e32 v18, 0x8000, v32
	v_add_u32_e32 v22, 0x8400, v32
	ds_read2_b32 v[10:11], v10 offset0:64 offset1:129
	ds_read2_b32 v[12:13], v12 offset0:66 offset1:131
	ds_read2_b32 v[14:15], v14 offset0:68 offset1:133
	ds_read2_b32 v[16:17], v16 offset0:70 offset1:135
	ds_read2_b32 v[18:19], v18 offset0:128 offset1:193
	ds_read2_b32 v[20:21], v22 offset0:2 offset1:67
	ds_read2_b32 v[22:23], v22 offset0:132 offset1:197
	v_add_u32_e32 v24, 0x8800, v32
	v_add_u32_e32 v26, 0xc200, v32
	v_add_u32_e32 v28, 0xc400, v32
	v_add_u32_e32 v30, 0xc600, v32
	v_add_u32_e32 v32, 0xc800, v32
	ds_read2_b32 v[24:25], v24 offset0:6 offset1:71
	ds_read2_b32 v[26:27], v26 offset0:64 offset1:129
	ds_read2_b32 v[28:29], v28 offset0:66 offset1:131
	ds_read2_b32 v[30:31], v30 offset0:68 offset1:133
	ds_read2_b32 v[32:33], v32 offset0:70 offset1:135
	s_waitcnt lgkmcnt(14)
	v_cvt_pk_bf16_f32 v0, v0, v1
	v_cvt_pk_bf16_f32 v1, v2, v3
	s_waitcnt lgkmcnt(13)
	v_cvt_pk_bf16_f32 v2, v6, v7
	s_waitcnt lgkmcnt(12)
	v_cvt_pk_bf16_f32 v3, v8, v9
	global_store_dwordx4 v[4:5], v[0:3], off
	s_mov_b64 s[0:1], 0
	s_waitcnt lgkmcnt(11)
	v_cvt_pk_bf16_f32 v0, v10, v11
	s_waitcnt lgkmcnt(10)
	v_cvt_pk_bf16_f32 v1, v12, v13
	s_waitcnt lgkmcnt(9)
	v_cvt_pk_bf16_f32 v2, v14, v15
	s_waitcnt lgkmcnt(8)
	v_cvt_pk_bf16_f32 v3, v16, v17
	global_store_dwordx4 v[4:5], v[0:3], off offset:128
	s_waitcnt lgkmcnt(7)
	s_nop 0
	v_cvt_pk_bf16_f32 v0, v18, v19
	s_waitcnt lgkmcnt(6)
	v_cvt_pk_bf16_f32 v1, v20, v21
	s_waitcnt lgkmcnt(5)
	v_cvt_pk_bf16_f32 v2, v22, v23
	s_waitcnt lgkmcnt(4)
	v_cvt_pk_bf16_f32 v3, v24, v25
	global_store_dwordx4 v[4:5], v[0:3], off offset:256
	s_waitcnt lgkmcnt(3)
	s_nop 0
	v_cvt_pk_bf16_f32 v0, v26, v27
	s_waitcnt lgkmcnt(2)
	v_cvt_pk_bf16_f32 v1, v28, v29
	s_waitcnt lgkmcnt(1)
	v_cvt_pk_bf16_f32 v2, v30, v31
	s_waitcnt lgkmcnt(0)
	v_cvt_pk_bf16_f32 v3, v32, v33
	global_store_dwordx4 v[4:5], v[0:3], off offset:384
	s_barrier
.LBB0_283:
	s_andn2_b64 vcc, exec, s[0:1]
	s_cbranch_vccnz .LBB0_280
	s_and_b32 s1, s3, 0x1fc0
	v_mov_b32_e32 v33, v224
	s_and_b32 s0, s2, 0xffffff00
	s_lshl_b32 s9, s1, 2
	v_readlane_b32 s14, v252, 20
	v_lshlrev_b32_e32 v0, 4, v33
	v_ashrrev_i32_e32 v34, 4, v33
	v_add_u32_e32 v4, 0x200, v33
	s_add_u32 s14, s14, s9
	v_readlane_b32 s9, v252, 21
	v_and_b32_e32 v192, 0xf0, v0
	v_add_u32_e32 v0, s0, v34
	v_ashrrev_i32_e32 v36, 4, v4
	v_add_u32_e32 v8, 0x400, v33
	s_addc_u32 s15, s9, 0
	s_waitcnt lgkmcnt(0)
	v_ashrrev_i32_e32 v1, 31, v0
	v_add_u32_e32 v4, s0, v36
	v_ashrrev_i32_e32 v37, 4, v8
	v_add_u32_e32 v12, 0x600, v33
	v_lshl_add_u64 v[28:29], s[14:15], 0, v[192:193]
	v_lshlrev_b64 v[0:1], 15, v[0:1]
	v_ashrrev_i32_e32 v5, 31, v4
	v_add_u32_e32 v8, s0, v37
	v_ashrrev_i32_e32 v38, 4, v12
	v_add_u32_e32 v16, 0x800, v33
	v_lshl_add_u64 v[0:1], v[28:29], 0, v[0:1]
	v_lshlrev_b64 v[4:5], 15, v[4:5]
	v_ashrrev_i32_e32 v9, 31, v8
	v_add_u32_e32 v12, s0, v38
	v_ashrrev_i32_e32 v39, 4, v16
	v_add_u32_e32 v20, 0xa00, v33
	global_load_dwordx4 v[0:3], v[0:1], off nt
	v_lshl_add_u64 v[4:5], v[28:29], 0, v[4:5]
	v_lshlrev_b64 v[8:9], 15, v[8:9]
	v_ashrrev_i32_e32 v13, 31, v12
	v_add_u32_e32 v16, s0, v39
	v_ashrrev_i32_e32 v40, 4, v20
	v_add_u32_e32 v24, 0xc00, v33
	global_load_dwordx4 v[4:7], v[4:5], off nt
	v_lshl_add_u64 v[8:9], v[28:29], 0, v[8:9]
	v_lshlrev_b64 v[12:13], 15, v[12:13]
	v_ashrrev_i32_e32 v17, 31, v16
	v_add_u32_e32 v20, s0, v40
	v_ashrrev_i32_e32 v41, 4, v24
	v_add_u32_e32 v30, 0xe00, v33
	global_load_dwordx4 v[8:11], v[8:9], off nt
	v_lshl_add_u64 v[12:13], v[28:29], 0, v[12:13]
	v_lshlrev_b64 v[16:17], 15, v[16:17]
	v_ashrrev_i32_e32 v21, 31, v20
	v_add_u32_e32 v24, s0, v41
	v_ashrrev_i32_e32 v42, 4, v30
	global_load_dwordx4 v[12:15], v[12:13], off nt
	v_lshl_add_u64 v[16:17], v[28:29], 0, v[16:17]
	v_lshlrev_b64 v[20:21], 15, v[20:21]
	v_ashrrev_i32_e32 v25, 31, v24
	v_add_u32_e32 v30, s0, v42
	global_load_dwordx4 v[16:19], v[16:17], off nt
	v_lshl_add_u64 v[20:21], v[28:29], 0, v[20:21]
	v_lshlrev_b64 v[24:25], 15, v[24:25]
	v_ashrrev_i32_e32 v31, 31, v30
	global_load_dwordx4 v[20:23], v[20:21], off nt
	v_lshl_add_u64 v[24:25], v[28:29], 0, v[24:25]
	v_lshlrev_b64 v[30:31], 15, v[30:31]
	global_load_dwordx4 v[24:27], v[24:25], off nt
	v_lshl_add_u64 v[28:29], v[28:29], 0, v[30:31]
	global_load_dwordx4 v[28:31], v[28:29], off nt
	v_add_u32_e32 v32, 0, v192
	v_mad_u64_u32 v[34:35], s[14:15], v34, s97, v[32:33]
	s_waitcnt vmcnt(0)
	ds_write2_b32 v34, v0, v1 offset1:1
	ds_write2_b32 v34, v2, v3 offset0:2 offset1:3
	v_mad_u64_u32 v[0:1], s[14:15], v36, s97, v[32:33]
	ds_write2_b32 v0, v4, v5 offset1:1
	ds_write2_b32 v0, v6, v7 offset0:2 offset1:3
	v_mad_u64_u32 v[0:1], s[14:15], v37, s97, v[32:33]
	ds_write2_b32 v0, v8, v9 offset1:1
	ds_write2_b32 v0, v10, v11 offset0:2 offset1:3
	v_mad_u64_u32 v[0:1], s[14:15], v38, s97, v[32:33]
	ds_write2_b32 v0, v12, v13 offset1:1
	ds_write2_b32 v0, v14, v15 offset0:2 offset1:3
	v_mad_u64_u32 v[0:1], s[14:15], v39, s97, v[32:33]
	ds_write2_b32 v0, v16, v17 offset1:1
	ds_write2_b32 v0, v18, v19 offset0:2 offset1:3
	v_mad_u64_u32 v[0:1], s[14:15], v40, s97, v[32:33]
	ds_write2_b32 v0, v20, v21 offset1:1
	ds_write2_b32 v0, v22, v23 offset0:2 offset1:3
	v_mad_u64_u32 v[0:1], s[14:15], v41, s97, v[32:33]
	ds_write2_b32 v0, v24, v25 offset1:1
	ds_write2_b32 v0, v26, v27 offset0:2 offset1:3
	v_mad_u64_u32 v[0:1], s[14:15], v42, s97, v[32:33]
	v_ashrrev_i32_e32 v2, 3, v33
	ds_write2_b32 v0, v28, v29 offset1:1
	ds_write2_b32 v0, v30, v31 offset0:2 offset1:3
	v_add_u32_e32 v0, s1, v2
	v_lshlrev_b32_e32 v3, 3, v33
	v_ashrrev_i32_e32 v1, 31, v0
	v_and_b32_e32 v3, 56, v3
	v_readlane_b32 s14, v252, 22
	v_lshlrev_b32_e32 v2, 2, v2
	v_mul_u32_u24_e32 v4, 0x104, v3
	v_lshlrev_b64 v[0:1], 12, v[0:1]
	v_readlane_b32 s15, v252, 23
	s_ashr_i32 s1, s0, 31
	v_add3_u32 v32, 0, v2, v4
	v_lshl_add_u64 v[0:1], s[14:15], 0, v[0:1]
	v_lshl_add_u64 v[0:1], s[0:1], 1, v[0:1]
	v_lshlrev_b32_e32 v192, 1, v3
	v_add_u32_e32 v8, 0x400, v32
	s_waitcnt lgkmcnt(0)
	s_barrier
	v_lshl_add_u64 v[4:5], v[0:1], 0, v[192:193]
	ds_read2_b32 v[0:1], v32 offset1:65
	ds_read2_b32 v[2:3], v32 offset0:130 offset1:195
	ds_read2_b32 v[6:7], v8 offset0:4 offset1:69
	ds_read2_b32 v[8:9], v8 offset0:134 offset1:199
	v_add_u32_e32 v10, 0x4000, v32
	v_add_u32_e32 v12, 0x4200, v32
	v_add_u32_e32 v14, 0x4400, v32
	v_add_u32_e32 v16, 0x4600, v32
	v_add_u32_e32 v18, 0x8000, v32
	v_add_u32_e32 v22, 0x8400, v32
	ds_read2_b32 v[10:11], v10 offset0:64 offset1:129
	ds_read2_b32 v[12:13], v12 offset0:66 offset1:131
	ds_read2_b32 v[14:15], v14 offset0:68 offset1:133
	ds_read2_b32 v[16:17], v16 offset0:70 offset1:135
	ds_read2_b32 v[18:19], v18 offset0:128 offset1:193
	ds_read2_b32 v[20:21], v22 offset0:2 offset1:67
	ds_read2_b32 v[22:23], v22 offset0:132 offset1:197
	v_add_u32_e32 v24, 0x8800, v32
	v_add_u32_e32 v26, 0xc200, v32
	v_add_u32_e32 v28, 0xc400, v32
	v_add_u32_e32 v30, 0xc600, v32
	v_add_u32_e32 v32, 0xc800, v32
	ds_read2_b32 v[24:25], v24 offset0:6 offset1:71
	ds_read2_b32 v[26:27], v26 offset0:64 offset1:129
	ds_read2_b32 v[28:29], v28 offset0:66 offset1:131
	ds_read2_b32 v[30:31], v30 offset0:68 offset1:133
	ds_read2_b32 v[32:33], v32 offset0:70 offset1:135
	s_waitcnt lgkmcnt(14)
	v_cvt_pk_bf16_f32 v0, v0, v1
	v_cvt_pk_bf16_f32 v1, v2, v3
	s_waitcnt lgkmcnt(13)
	v_cvt_pk_bf16_f32 v2, v6, v7
	s_waitcnt lgkmcnt(12)
	v_cvt_pk_bf16_f32 v3, v8, v9
	global_store_dwordx4 v[4:5], v[0:3], off
	s_waitcnt lgkmcnt(11)
	s_nop 0
	v_cvt_pk_bf16_f32 v0, v10, v11
	s_waitcnt lgkmcnt(10)
	v_cvt_pk_bf16_f32 v1, v12, v13
	s_waitcnt lgkmcnt(9)
	v_cvt_pk_bf16_f32 v2, v14, v15
	s_waitcnt lgkmcnt(8)
	v_cvt_pk_bf16_f32 v3, v16, v17
	global_store_dwordx4 v[4:5], v[0:3], off offset:128
	s_waitcnt lgkmcnt(7)
	s_nop 0
	v_cvt_pk_bf16_f32 v0, v18, v19
	s_waitcnt lgkmcnt(6)
	v_cvt_pk_bf16_f32 v1, v20, v21
	s_waitcnt lgkmcnt(5)
	v_cvt_pk_bf16_f32 v2, v22, v23
	s_waitcnt lgkmcnt(4)
	v_cvt_pk_bf16_f32 v3, v24, v25
	global_store_dwordx4 v[4:5], v[0:3], off offset:256
	s_waitcnt lgkmcnt(3)
	s_nop 0
	v_cvt_pk_bf16_f32 v0, v26, v27
	s_waitcnt lgkmcnt(2)
	v_cvt_pk_bf16_f32 v1, v28, v29
	s_waitcnt lgkmcnt(1)
	v_cvt_pk_bf16_f32 v2, v30, v31
	s_waitcnt lgkmcnt(0)
	v_cvt_pk_bf16_f32 v3, v32, v33
	global_store_dwordx4 v[4:5], v[0:3], off offset:384
	s_barrier
	s_branch .LBB0_280

.LBB0_286:
	s_addk_i32 s2, 0x80
	s_cmpk_gt_i32 s2, 0x3ff
	s_mov_b64 s[0:1], -1
	s_cbranch_scc0 .LBB0_288
	s_and_b32 s0, s5, 0x7fffff00
	s_add_i32 s64, s0, 0xffffe000
	s_and_b32 s0, s4, 0x7c0
	v_mov_b32_e32 v33, v224
	s_lshl_b32 s1, s0, 2
	v_lshlrev_b32_e32 v0, 4, v33
	v_ashrrev_i32_e32 v34, 4, v33
	v_add_u32_e32 v4, 0x200, v33
	s_add_u32 s14, s55, s1
	v_and_b32_e32 v192, 0xf0, v0
	v_add_u32_e32 v0, s64, v34
	v_ashrrev_i32_e32 v36, 4, v4
	v_add_u32_e32 v8, 0x400, v33
	s_addc_u32 s15, s58, 0
	s_waitcnt lgkmcnt(0)
	v_ashrrev_i32_e32 v1, 31, v0
	v_add_u32_e32 v4, s64, v36
	v_ashrrev_i32_e32 v37, 4, v8
	v_add_u32_e32 v12, 0x600, v33
	v_lshl_add_u64 v[28:29], s[14:15], 0, v[192:193]
	v_lshlrev_b64 v[0:1], 13, v[0:1]
	v_ashrrev_i32_e32 v5, 31, v4
	v_add_u32_e32 v8, s64, v37
	v_ashrrev_i32_e32 v38, 4, v12
	v_add_u32_e32 v16, 0x800, v33
	v_lshl_add_u64 v[0:1], v[28:29], 0, v[0:1]
	v_lshlrev_b64 v[4:5], 13, v[4:5]
	v_ashrrev_i32_e32 v9, 31, v8
	v_add_u32_e32 v12, s64, v38
	v_ashrrev_i32_e32 v39, 4, v16
	v_add_u32_e32 v20, 0xa00, v33
	global_load_dwordx4 v[0:3], v[0:1], off nt
	v_lshl_add_u64 v[4:5], v[28:29], 0, v[4:5]
	v_lshlrev_b64 v[8:9], 13, v[8:9]
	v_ashrrev_i32_e32 v13, 31, v12
	v_add_u32_e32 v16, s64, v39
	v_ashrrev_i32_e32 v40, 4, v20
	v_add_u32_e32 v24, 0xc00, v33
	global_load_dwordx4 v[4:7], v[4:5], off nt
	v_lshl_add_u64 v[8:9], v[28:29], 0, v[8:9]
	v_lshlrev_b64 v[12:13], 13, v[12:13]
	v_ashrrev_i32_e32 v17, 31, v16
	v_add_u32_e32 v20, s64, v40
	v_ashrrev_i32_e32 v41, 4, v24
	v_add_u32_e32 v30, 0xe00, v33
	global_load_dwordx4 v[8:11], v[8:9], off nt
	v_lshl_add_u64 v[12:13], v[28:29], 0, v[12:13]
	v_lshlrev_b64 v[16:17], 13, v[16:17]
	v_ashrrev_i32_e32 v21, 31, v20
	v_add_u32_e32 v24, s64, v41
	v_ashrrev_i32_e32 v42, 4, v30
	global_load_dwordx4 v[12:15], v[12:13], off nt
	v_lshl_add_u64 v[16:17], v[28:29], 0, v[16:17]
	v_lshlrev_b64 v[20:21], 13, v[20:21]
	v_ashrrev_i32_e32 v25, 31, v24
	v_add_u32_e32 v30, s64, v42
	global_load_dwordx4 v[16:19], v[16:17], off nt
	v_lshl_add_u64 v[20:21], v[28:29], 0, v[20:21]
	v_lshlrev_b64 v[24:25], 13, v[24:25]
	v_ashrrev_i32_e32 v31, 31, v30
	global_load_dwordx4 v[20:23], v[20:21], off nt
	v_lshl_add_u64 v[24:25], v[28:29], 0, v[24:25]
	v_lshlrev_b64 v[30:31], 13, v[30:31]
	global_load_dwordx4 v[24:27], v[24:25], off nt
	v_lshl_add_u64 v[28:29], v[28:29], 0, v[30:31]
	global_load_dwordx4 v[28:31], v[28:29], off nt
	v_add_u32_e32 v32, 0, v192
	v_mad_u64_u32 v[34:35], s[14:15], v34, s97, v[32:33]
	s_waitcnt vmcnt(0)
	ds_write2_b32 v34, v0, v1 offset1:1
	ds_write2_b32 v34, v2, v3 offset0:2 offset1:3
	v_mad_u64_u32 v[0:1], s[14:15], v36, s97, v[32:33]
	ds_write2_b32 v0, v4, v5 offset1:1
	ds_write2_b32 v0, v6, v7 offset0:2 offset1:3
	v_mad_u64_u32 v[0:1], s[14:15], v37, s97, v[32:33]
	ds_write2_b32 v0, v8, v9 offset1:1
	ds_write2_b32 v0, v10, v11 offset0:2 offset1:3
	v_mad_u64_u32 v[0:1], s[14:15], v38, s97, v[32:33]
	ds_write2_b32 v0, v12, v13 offset1:1
	ds_write2_b32 v0, v14, v15 offset0:2 offset1:3
	v_mad_u64_u32 v[0:1], s[14:15], v39, s97, v[32:33]
	ds_write2_b32 v0, v16, v17 offset1:1
	ds_write2_b32 v0, v18, v19 offset0:2 offset1:3
	v_mad_u64_u32 v[0:1], s[14:15], v40, s97, v[32:33]
	ds_write2_b32 v0, v20, v21 offset1:1
	ds_write2_b32 v0, v22, v23 offset0:2 offset1:3
	v_mad_u64_u32 v[0:1], s[14:15], v41, s97, v[32:33]
	ds_write2_b32 v0, v24, v25 offset1:1
	ds_write2_b32 v0, v26, v27 offset0:2 offset1:3
	v_mad_u64_u32 v[0:1], s[14:15], v42, s97, v[32:33]
	v_ashrrev_i32_e32 v2, 3, v33
	ds_write2_b32 v0, v28, v29 offset1:1
	ds_write2_b32 v0, v30, v31 offset0:2 offset1:3
	v_add_u32_e32 v0, s0, v2
	v_lshlrev_b32_e32 v3, 3, v33
	v_ashrrev_i32_e32 v1, 31, v0
	v_and_b32_e32 v3, 56, v3
	v_lshlrev_b32_e32 v2, 2, v2
	v_mul_u32_u24_e32 v4, 0x104, v3
	v_lshlrev_b64 v[0:1], 14, v[0:1]
	v_add3_u32 v32, 0, v2, v4
	v_lshl_add_u64 v[0:1], s[62:63], 0, v[0:1]
	v_lshl_add_u64 v[0:1], s[64:65], 1, v[0:1]
	v_lshlrev_b32_e32 v192, 1, v3
	v_add_u32_e32 v8, 0x400, v32
	s_waitcnt lgkmcnt(0)
	s_barrier
	v_lshl_add_u64 v[4:5], v[0:1], 0, v[192:193]
	ds_read2_b32 v[0:1], v32 offset1:65
	ds_read2_b32 v[2:3], v32 offset0:130 offset1:195
	ds_read2_b32 v[6:7], v8 offset0:4 offset1:69
	ds_read2_b32 v[8:9], v8 offset0:134 offset1:199
	v_add_u32_e32 v10, 0x4000, v32
	v_add_u32_e32 v12, 0x4200, v32
	v_add_u32_e32 v14, 0x4400, v32
	v_add_u32_e32 v16, 0x4600, v32
	v_add_u32_e32 v18, 0x8000, v32
	v_add_u32_e32 v22, 0x8400, v32
	ds_read2_b32 v[10:11], v10 offset0:64 offset1:129
	ds_read2_b32 v[12:13], v12 offset0:66 offset1:131
	ds_read2_b32 v[14:15], v14 offset0:68 offset1:133
	ds_read2_b32 v[16:17], v16 offset0:70 offset1:135
	ds_read2_b32 v[18:19], v18 offset0:128 offset1:193
	ds_read2_b32 v[20:21], v22 offset0:2 offset1:67
	ds_read2_b32 v[22:23], v22 offset0:132 offset1:197
	v_add_u32_e32 v24, 0x8800, v32
	v_add_u32_e32 v26, 0xc200, v32
	v_add_u32_e32 v28, 0xc400, v32
	v_add_u32_e32 v30, 0xc600, v32
	v_add_u32_e32 v32, 0xc800, v32
	ds_read2_b32 v[24:25], v24 offset0:6 offset1:71
	ds_read2_b32 v[26:27], v26 offset0:64 offset1:129
	ds_read2_b32 v[28:29], v28 offset0:66 offset1:131
	ds_read2_b32 v[30:31], v30 offset0:68 offset1:133
	ds_read2_b32 v[32:33], v32 offset0:70 offset1:135
	s_waitcnt lgkmcnt(14)
	v_cvt_pk_bf16_f32 v0, v0, v1
	v_cvt_pk_bf16_f32 v1, v2, v3
	s_waitcnt lgkmcnt(13)
	v_cvt_pk_bf16_f32 v2, v6, v7
	s_waitcnt lgkmcnt(12)
	v_cvt_pk_bf16_f32 v3, v8, v9
	global_store_dwordx4 v[4:5], v[0:3], off
	s_mov_b64 s[0:1], 0
	s_waitcnt lgkmcnt(11)
	v_cvt_pk_bf16_f32 v0, v10, v11
	s_waitcnt lgkmcnt(10)
	v_cvt_pk_bf16_f32 v1, v12, v13
	s_waitcnt lgkmcnt(9)
	v_cvt_pk_bf16_f32 v2, v14, v15
	s_waitcnt lgkmcnt(8)
	v_cvt_pk_bf16_f32 v3, v16, v17
	global_store_dwordx4 v[4:5], v[0:3], off offset:128
	s_waitcnt lgkmcnt(7)
	s_nop 0
	v_cvt_pk_bf16_f32 v0, v18, v19
	s_waitcnt lgkmcnt(6)
	v_cvt_pk_bf16_f32 v1, v20, v21
	s_waitcnt lgkmcnt(5)
	v_cvt_pk_bf16_f32 v2, v22, v23
	s_waitcnt lgkmcnt(4)
	v_cvt_pk_bf16_f32 v3, v24, v25
	global_store_dwordx4 v[4:5], v[0:3], off offset:256
	s_waitcnt lgkmcnt(3)
	s_nop 0
	v_cvt_pk_bf16_f32 v0, v26, v27
	s_waitcnt lgkmcnt(2)
	v_cvt_pk_bf16_f32 v1, v28, v29
	s_waitcnt lgkmcnt(1)
	v_cvt_pk_bf16_f32 v2, v30, v31
	s_waitcnt lgkmcnt(0)
	v_cvt_pk_bf16_f32 v3, v32, v33
	global_store_dwordx4 v[4:5], v[0:3], off offset:384
	s_barrier
.LBB0_288:
	s_andn2_b64 vcc, exec, s[0:1]
	s_cbranch_vccnz .LBB0_285
	s_and_b32 s1, s4, 0x1fc0
	v_mov_b32_e32 v33, v224
	s_and_b32 s0, s3, 0x7fffff00
	s_lshl_b32 s9, s1, 2
	v_readlane_b32 s14, v252, 20
	v_lshlrev_b32_e32 v0, 4, v33
	v_ashrrev_i32_e32 v34, 4, v33
	v_add_u32_e32 v4, 0x200, v33
	s_add_u32 s14, s14, s9
	v_readlane_b32 s9, v252, 21
	v_and_b32_e32 v192, 0xf0, v0
	v_add_u32_e32 v0, s0, v34
	v_ashrrev_i32_e32 v36, 4, v4
	v_add_u32_e32 v8, 0x400, v33
	s_addc_u32 s15, s9, 0
	s_waitcnt lgkmcnt(0)
	v_ashrrev_i32_e32 v1, 31, v0
	v_add_u32_e32 v4, s0, v36
	v_ashrrev_i32_e32 v37, 4, v8
	v_add_u32_e32 v12, 0x600, v33
	v_lshl_add_u64 v[28:29], s[14:15], 0, v[192:193]
	v_lshlrev_b64 v[0:1], 15, v[0:1]
	v_ashrrev_i32_e32 v5, 31, v4
	v_add_u32_e32 v8, s0, v37
	v_ashrrev_i32_e32 v38, 4, v12
	v_add_u32_e32 v16, 0x800, v33
	v_lshl_add_u64 v[0:1], v[28:29], 0, v[0:1]
	v_lshlrev_b64 v[4:5], 15, v[4:5]
	v_ashrrev_i32_e32 v9, 31, v8
	v_add_u32_e32 v12, s0, v38
	v_ashrrev_i32_e32 v39, 4, v16
	v_add_u32_e32 v20, 0xa00, v33
	global_load_dwordx4 v[0:3], v[0:1], off nt
	v_lshl_add_u64 v[4:5], v[28:29], 0, v[4:5]
	v_lshlrev_b64 v[8:9], 15, v[8:9]
	v_ashrrev_i32_e32 v13, 31, v12
	v_add_u32_e32 v16, s0, v39
	v_ashrrev_i32_e32 v40, 4, v20
	v_add_u32_e32 v24, 0xc00, v33
	global_load_dwordx4 v[4:7], v[4:5], off nt
	v_lshl_add_u64 v[8:9], v[28:29], 0, v[8:9]
	v_lshlrev_b64 v[12:13], 15, v[12:13]
	v_ashrrev_i32_e32 v17, 31, v16
	v_add_u32_e32 v20, s0, v40
	v_ashrrev_i32_e32 v41, 4, v24
	v_add_u32_e32 v30, 0xe00, v33
	global_load_dwordx4 v[8:11], v[8:9], off nt
	v_lshl_add_u64 v[12:13], v[28:29], 0, v[12:13]
	v_lshlrev_b64 v[16:17], 15, v[16:17]
	v_ashrrev_i32_e32 v21, 31, v20
	v_add_u32_e32 v24, s0, v41
	v_ashrrev_i32_e32 v42, 4, v30
	global_load_dwordx4 v[12:15], v[12:13], off nt
	v_lshl_add_u64 v[16:17], v[28:29], 0, v[16:17]
	v_lshlrev_b64 v[20:21], 15, v[20:21]
	v_ashrrev_i32_e32 v25, 31, v24
	v_add_u32_e32 v30, s0, v42
	global_load_dwordx4 v[16:19], v[16:17], off nt
	v_lshl_add_u64 v[20:21], v[28:29], 0, v[20:21]
	v_lshlrev_b64 v[24:25], 15, v[24:25]
	v_ashrrev_i32_e32 v31, 31, v30
	global_load_dwordx4 v[20:23], v[20:21], off nt
	v_lshl_add_u64 v[24:25], v[28:29], 0, v[24:25]
	v_lshlrev_b64 v[30:31], 15, v[30:31]
	global_load_dwordx4 v[24:27], v[24:25], off nt
	v_lshl_add_u64 v[28:29], v[28:29], 0, v[30:31]
	global_load_dwordx4 v[28:31], v[28:29], off nt
	v_add_u32_e32 v32, 0, v192
	v_mad_u64_u32 v[34:35], s[14:15], v34, s97, v[32:33]
	s_lshl_b32 s64, s0, 1
	s_waitcnt vmcnt(0)
	ds_write2_b32 v34, v0, v1 offset1:1
	ds_write2_b32 v34, v2, v3 offset0:2 offset1:3
	v_mad_u64_u32 v[0:1], s[14:15], v36, s97, v[32:33]
	ds_write2_b32 v0, v4, v5 offset1:1
	ds_write2_b32 v0, v6, v7 offset0:2 offset1:3
	v_mad_u64_u32 v[0:1], s[14:15], v37, s97, v[32:33]
	ds_write2_b32 v0, v8, v9 offset1:1
	ds_write2_b32 v0, v10, v11 offset0:2 offset1:3
	v_mad_u64_u32 v[0:1], s[14:15], v38, s97, v[32:33]
	ds_write2_b32 v0, v12, v13 offset1:1
	ds_write2_b32 v0, v14, v15 offset0:2 offset1:3
	v_mad_u64_u32 v[0:1], s[14:15], v39, s97, v[32:33]
	ds_write2_b32 v0, v16, v17 offset1:1
	ds_write2_b32 v0, v18, v19 offset0:2 offset1:3
	v_mad_u64_u32 v[0:1], s[14:15], v40, s97, v[32:33]
	ds_write2_b32 v0, v20, v21 offset1:1
	ds_write2_b32 v0, v22, v23 offset0:2 offset1:3
	v_mad_u64_u32 v[0:1], s[14:15], v41, s97, v[32:33]
	ds_write2_b32 v0, v24, v25 offset1:1
	ds_write2_b32 v0, v26, v27 offset0:2 offset1:3
	v_mad_u64_u32 v[0:1], s[14:15], v42, s97, v[32:33]
	v_ashrrev_i32_e32 v2, 3, v33
	ds_write2_b32 v0, v28, v29 offset1:1
	ds_write2_b32 v0, v30, v31 offset0:2 offset1:3
	v_add_u32_e32 v0, s1, v2
	v_lshlrev_b32_e32 v3, 3, v33
	v_ashrrev_i32_e32 v1, 31, v0
	v_and_b32_e32 v3, 56, v3
	v_readlane_b32 s14, v252, 22
	v_lshlrev_b32_e32 v2, 2, v2
	v_mul_u32_u24_e32 v4, 0x104, v3
	v_lshlrev_b64 v[0:1], 12, v[0:1]
	v_readlane_b32 s15, v252, 23
	v_add3_u32 v32, 0, v2, v4
	v_lshlrev_b32_e32 v192, 1, v3
	v_lshl_add_u64 v[0:1], s[14:15], 0, v[0:1]
	v_lshl_add_u64 v[0:1], v[0:1], 0, s[64:65]
	v_add_u32_e32 v8, 0x400, v32
	s_waitcnt lgkmcnt(0)
	s_barrier
	v_lshl_add_u64 v[4:5], v[0:1], 0, v[192:193]
	ds_read2_b32 v[0:1], v32 offset1:65
	ds_read2_b32 v[2:3], v32 offset0:130 offset1:195
	ds_read2_b32 v[6:7], v8 offset0:4 offset1:69
	ds_read2_b32 v[8:9], v8 offset0:134 offset1:199
	v_add_u32_e32 v10, 0x4000, v32
	v_add_u32_e32 v12, 0x4200, v32
	v_add_u32_e32 v14, 0x4400, v32
	v_add_u32_e32 v16, 0x4600, v32
	v_add_u32_e32 v18, 0x8000, v32
	v_add_u32_e32 v22, 0x8400, v32
	ds_read2_b32 v[10:11], v10 offset0:64 offset1:129
	ds_read2_b32 v[12:13], v12 offset0:66 offset1:131
	ds_read2_b32 v[14:15], v14 offset0:68 offset1:133
	ds_read2_b32 v[16:17], v16 offset0:70 offset1:135
	ds_read2_b32 v[18:19], v18 offset0:128 offset1:193
	ds_read2_b32 v[20:21], v22 offset0:2 offset1:67
	ds_read2_b32 v[22:23], v22 offset0:132 offset1:197
	v_add_u32_e32 v24, 0x8800, v32
	v_add_u32_e32 v26, 0xc200, v32
	v_add_u32_e32 v28, 0xc400, v32
	v_add_u32_e32 v30, 0xc600, v32
	v_add_u32_e32 v32, 0xc800, v32
	ds_read2_b32 v[24:25], v24 offset0:6 offset1:71
	ds_read2_b32 v[26:27], v26 offset0:64 offset1:129
	ds_read2_b32 v[28:29], v28 offset0:66 offset1:131
	ds_read2_b32 v[30:31], v30 offset0:68 offset1:133
	ds_read2_b32 v[32:33], v32 offset0:70 offset1:135
	s_waitcnt lgkmcnt(14)
	v_cvt_pk_bf16_f32 v0, v0, v1
	v_cvt_pk_bf16_f32 v1, v2, v3
	s_waitcnt lgkmcnt(13)
	v_cvt_pk_bf16_f32 v2, v6, v7
	s_waitcnt lgkmcnt(12)
	v_cvt_pk_bf16_f32 v3, v8, v9
	global_store_dwordx4 v[4:5], v[0:3], off
	s_waitcnt lgkmcnt(11)
	s_nop 0
	v_cvt_pk_bf16_f32 v0, v10, v11
	s_waitcnt lgkmcnt(10)
	v_cvt_pk_bf16_f32 v1, v12, v13
	s_waitcnt lgkmcnt(9)
	v_cvt_pk_bf16_f32 v2, v14, v15
	s_waitcnt lgkmcnt(8)
	v_cvt_pk_bf16_f32 v3, v16, v17
	global_store_dwordx4 v[4:5], v[0:3], off offset:128
	s_waitcnt lgkmcnt(7)
	s_nop 0
	v_cvt_pk_bf16_f32 v0, v18, v19
	s_waitcnt lgkmcnt(6)
	v_cvt_pk_bf16_f32 v1, v20, v21
	s_waitcnt lgkmcnt(5)
	v_cvt_pk_bf16_f32 v2, v22, v23
	s_waitcnt lgkmcnt(4)
	v_cvt_pk_bf16_f32 v3, v24, v25
	global_store_dwordx4 v[4:5], v[0:3], off offset:256
	s_waitcnt lgkmcnt(3)
	s_nop 0
	v_cvt_pk_bf16_f32 v0, v26, v27
	s_waitcnt lgkmcnt(2)
	v_cvt_pk_bf16_f32 v1, v28, v29
	s_waitcnt lgkmcnt(1)
	v_cvt_pk_bf16_f32 v2, v30, v31
	s_waitcnt lgkmcnt(0)
	v_cvt_pk_bf16_f32 v3, v32, v33
	global_store_dwordx4 v[4:5], v[0:3], off offset:384
	s_barrier
	s_branch .LBB0_285

.LBB0_546:
	s_and_b32 s0, s3, 0xffffff00
	s_and_b32 s1, s2, 0x7c0
	v_mov_b32_e32 v33, v224
	s_addk_i32 s0, 0xe000
	s_lshl_b32 s5, s1, 2
	v_lshlrev_b32_e32 v0, 4, v33
	v_ashrrev_i32_e32 v34, 4, v33
	v_add_u32_e32 v4, 0x200, v33
	s_add_u32 s10, s55, s5
	v_and_b32_e32 v192, 0xf0, v0
	v_add_u32_e32 v0, s0, v34
	v_ashrrev_i32_e32 v36, 4, v4
	v_add_u32_e32 v8, 0x400, v33
	s_addc_u32 s11, s58, 0
	v_ashrrev_i32_e32 v1, 31, v0
	v_add_u32_e32 v4, s0, v36
	v_ashrrev_i32_e32 v37, 4, v8
	v_add_u32_e32 v12, 0x600, v33
	v_lshl_add_u64 v[28:29], s[10:11], 0, v[192:193]
	v_lshlrev_b64 v[0:1], 13, v[0:1]
	v_ashrrev_i32_e32 v5, 31, v4
	v_add_u32_e32 v8, s0, v37
	v_ashrrev_i32_e32 v38, 4, v12
	v_add_u32_e32 v16, 0x800, v33
	v_lshl_add_u64 v[0:1], v[28:29], 0, v[0:1]
	v_lshlrev_b64 v[4:5], 13, v[4:5]
	v_ashrrev_i32_e32 v9, 31, v8
	v_add_u32_e32 v12, s0, v38
	v_ashrrev_i32_e32 v39, 4, v16
	v_add_u32_e32 v20, 0xa00, v33
	global_load_dwordx4 v[0:3], v[0:1], off nt
	v_lshl_add_u64 v[4:5], v[28:29], 0, v[4:5]
	v_lshlrev_b64 v[8:9], 13, v[8:9]
	v_ashrrev_i32_e32 v13, 31, v12
	v_add_u32_e32 v16, s0, v39
	v_ashrrev_i32_e32 v40, 4, v20
	v_add_u32_e32 v24, 0xc00, v33
	global_load_dwordx4 v[4:7], v[4:5], off nt
	v_lshl_add_u64 v[8:9], v[28:29], 0, v[8:9]
	v_lshlrev_b64 v[12:13], 13, v[12:13]
	v_ashrrev_i32_e32 v17, 31, v16
	v_add_u32_e32 v20, s0, v40
	v_ashrrev_i32_e32 v41, 4, v24
	v_add_u32_e32 v30, 0xe00, v33
	global_load_dwordx4 v[8:11], v[8:9], off nt
	v_lshl_add_u64 v[12:13], v[28:29], 0, v[12:13]
	v_lshlrev_b64 v[16:17], 13, v[16:17]
	v_ashrrev_i32_e32 v21, 31, v20
	v_add_u32_e32 v24, s0, v41
	v_ashrrev_i32_e32 v42, 4, v30
	global_load_dwordx4 v[12:15], v[12:13], off nt
	v_lshl_add_u64 v[16:17], v[28:29], 0, v[16:17]
	v_lshlrev_b64 v[20:21], 13, v[20:21]
	v_ashrrev_i32_e32 v25, 31, v24
	v_add_u32_e32 v30, s0, v42
	global_load_dwordx4 v[16:19], v[16:17], off nt
	v_lshl_add_u64 v[20:21], v[28:29], 0, v[20:21]
	v_lshlrev_b64 v[24:25], 13, v[24:25]
	v_ashrrev_i32_e32 v31, 31, v30
	global_load_dwordx4 v[20:23], v[20:21], off nt
	v_lshl_add_u64 v[24:25], v[28:29], 0, v[24:25]
	v_lshlrev_b64 v[30:31], 13, v[30:31]
	global_load_dwordx4 v[24:27], v[24:25], off nt
	v_lshl_add_u64 v[28:29], v[28:29], 0, v[30:31]
	global_load_dwordx4 v[28:31], v[28:29], off nt
	v_add_u32_e32 v32, 0, v192
	v_mad_u64_u32 v[34:35], s[10:11], v34, s97, v[32:33]
	s_add_i32 s4, s4, 48
	s_addk_i32 s3, 0x180
	s_addk_i32 s2, 0xc00
	s_waitcnt vmcnt(0)
	ds_write2_b32 v34, v0, v1 offset1:1
	ds_write2_b32 v34, v2, v3 offset0:2 offset1:3
	v_mad_u64_u32 v[0:1], s[10:11], v36, s97, v[32:33]
	ds_write2_b32 v0, v4, v5 offset1:1
	ds_write2_b32 v0, v6, v7 offset0:2 offset1:3
	v_mad_u64_u32 v[0:1], s[10:11], v37, s97, v[32:33]
	ds_write2_b32 v0, v8, v9 offset1:1
	ds_write2_b32 v0, v10, v11 offset0:2 offset1:3
	v_mad_u64_u32 v[0:1], s[10:11], v38, s97, v[32:33]
	ds_write2_b32 v0, v12, v13 offset1:1
	ds_write2_b32 v0, v14, v15 offset0:2 offset1:3
	v_mad_u64_u32 v[0:1], s[10:11], v39, s97, v[32:33]
	ds_write2_b32 v0, v16, v17 offset1:1
	ds_write2_b32 v0, v18, v19 offset0:2 offset1:3
	v_mad_u64_u32 v[0:1], s[10:11], v40, s97, v[32:33]
	ds_write2_b32 v0, v20, v21 offset1:1
	ds_write2_b32 v0, v22, v23 offset0:2 offset1:3
	v_mad_u64_u32 v[0:1], s[10:11], v41, s97, v[32:33]
	ds_write2_b32 v0, v24, v25 offset1:1
	ds_write2_b32 v0, v26, v27 offset0:2 offset1:3
	v_mad_u64_u32 v[0:1], s[10:11], v42, s97, v[32:33]
	v_ashrrev_i32_e32 v2, 3, v33
	ds_write2_b32 v0, v28, v29 offset1:1
	ds_write2_b32 v0, v30, v31 offset0:2 offset1:3
	v_add_u32_e32 v0, s1, v2
	v_lshlrev_b32_e32 v3, 3, v33
	v_ashrrev_i32_e32 v1, 31, v0
	v_and_b32_e32 v3, 56, v3
	v_lshlrev_b32_e32 v2, 2, v2
	v_mul_u32_u24_e32 v4, 0x104, v3
	v_lshlrev_b64 v[0:1], 14, v[0:1]
	s_ashr_i32 s1, s0, 31
	v_add3_u32 v32, 0, v2, v4
	v_lshl_add_u64 v[0:1], s[62:63], 0, v[0:1]
	v_lshl_add_u64 v[0:1], s[0:1], 1, v[0:1]
	v_lshlrev_b32_e32 v192, 1, v3
	v_add_u32_e32 v8, 0x400, v32
	s_waitcnt lgkmcnt(0)
	s_barrier
	v_lshl_add_u64 v[4:5], v[0:1], 0, v[192:193]
	ds_read2_b32 v[0:1], v32 offset1:65
	ds_read2_b32 v[2:3], v32 offset0:130 offset1:195
	ds_read2_b32 v[6:7], v8 offset0:4 offset1:69
	ds_read2_b32 v[8:9], v8 offset0:134 offset1:199
	v_add_u32_e32 v10, 0x4000, v32
	v_add_u32_e32 v12, 0x4200, v32
	v_add_u32_e32 v14, 0x4400, v32
	v_add_u32_e32 v16, 0x4600, v32
	v_add_u32_e32 v18, 0x8000, v32
	v_add_u32_e32 v22, 0x8400, v32
	ds_read2_b32 v[10:11], v10 offset0:64 offset1:129
	ds_read2_b32 v[12:13], v12 offset0:66 offset1:131
	ds_read2_b32 v[14:15], v14 offset0:68 offset1:133
	ds_read2_b32 v[16:17], v16 offset0:70 offset1:135
	ds_read2_b32 v[18:19], v18 offset0:128 offset1:193
	ds_read2_b32 v[20:21], v22 offset0:2 offset1:67
	ds_read2_b32 v[22:23], v22 offset0:132 offset1:197
	v_add_u32_e32 v24, 0x8800, v32
	v_add_u32_e32 v26, 0xc200, v32
	v_add_u32_e32 v28, 0xc400, v32
	v_add_u32_e32 v30, 0xc600, v32
	v_add_u32_e32 v32, 0xc800, v32
	ds_read2_b32 v[24:25], v24 offset0:6 offset1:71
	ds_read2_b32 v[26:27], v26 offset0:64 offset1:129
	ds_read2_b32 v[28:29], v28 offset0:66 offset1:131
	ds_read2_b32 v[30:31], v30 offset0:68 offset1:133
	ds_read2_b32 v[32:33], v32 offset0:70 offset1:135
	s_waitcnt lgkmcnt(14)
	v_cvt_pk_bf16_f32 v0, v0, v1
	v_cvt_pk_bf16_f32 v1, v2, v3
	s_waitcnt lgkmcnt(13)
	v_cvt_pk_bf16_f32 v2, v6, v7
	s_waitcnt lgkmcnt(12)
	v_cvt_pk_bf16_f32 v3, v8, v9
	global_store_dwordx4 v[4:5], v[0:3], off
	s_cmpk_gt_i32 s4, 0x7cf
	s_waitcnt lgkmcnt(11)
	v_cvt_pk_bf16_f32 v0, v10, v11
	s_waitcnt lgkmcnt(10)
	v_cvt_pk_bf16_f32 v1, v12, v13
	s_waitcnt lgkmcnt(9)
	v_cvt_pk_bf16_f32 v2, v14, v15
	s_waitcnt lgkmcnt(8)
	v_cvt_pk_bf16_f32 v3, v16, v17
	global_store_dwordx4 v[4:5], v[0:3], off offset:128
	s_waitcnt lgkmcnt(7)
	s_nop 0
	v_cvt_pk_bf16_f32 v0, v18, v19
	s_waitcnt lgkmcnt(6)
	v_cvt_pk_bf16_f32 v1, v20, v21
	s_waitcnt lgkmcnt(5)
	v_cvt_pk_bf16_f32 v2, v22, v23
	s_waitcnt lgkmcnt(4)
	v_cvt_pk_bf16_f32 v3, v24, v25
	global_store_dwordx4 v[4:5], v[0:3], off offset:256
	s_waitcnt lgkmcnt(3)
	s_nop 0
	v_cvt_pk_bf16_f32 v0, v26, v27
	s_waitcnt lgkmcnt(2)
	v_cvt_pk_bf16_f32 v1, v28, v29
	s_waitcnt lgkmcnt(1)
	v_cvt_pk_bf16_f32 v2, v30, v31
	s_waitcnt lgkmcnt(0)
	v_cvt_pk_bf16_f32 v3, v32, v33
	global_store_dwordx4 v[4:5], v[0:3], off offset:384
	s_barrier
	s_cbranch_scc0 .LBB0_546

.LBB0_613:
	s_andn2_b64 vcc, exec, s[2:3]
	s_cbranch_vccnz .LBB0_639
	s_add_i32 s2, s67, 0xfffffd00
	s_add_i32 s3, s67, 0xfffff200
	s_cmpk_lt_u32 s2, 0xb00
	s_cselect_b32 s28, s2, s3
	s_cmpk_lt_u32 s3, 0xb00
	s_cselect_b64 s[4:5], -1, 0
	s_add_i32 s3, s28, 0xfffffd00
	s_cmp_lt_u32 s3, 0xffffff00
	s_cselect_b64 s[14:15], -1, 0
	s_and_b64 s[4:5], s[4:5], s[14:15]
	s_and_b64 vcc, exec, s[4:5]
	s_cbranch_vccnz .LBB0_639
	s_cmpk_gt_u32 s2, 0xaff
	s_cselect_b64 s[14:15], -1, 0
	s_cmpk_gt_u32 s28, 0x1ff
	s_mov_b64 s[2:3], -1
	s_cbranch_scc0 .LBB0_629
	s_cmpk_gt_u32 s28, 0x2ff
	s_cbranch_scc0 .LBB0_622
	s_and_b64 s[2:3], s[14:15], exec
	s_cselect_b32 s35, 0x4000000, 0
	s_lshl_b32 s29, s28, 6
	s_and_b64 s[2:3], s[14:15], exec
	s_cselect_b32 s34, 0x2000000, 0
	s_cmpk_gt_u32 s28, 0x6ff
	s_mov_b64 s[2:3], -1
	s_cbranch_scc0 .LBB0_619
	s_add_u32 s3, s22, s35
	s_addc_u32 s47, s23, 0
	s_lshl_b32 s2, s28, 3
	s_and_b32 s2, s2, 0x7f00
	s_addk_i32 s2, 0xc800
	s_and_b32 s64, s29, 0x7c0
	v_readlane_b32 s4, v251, 63
	v_mov_b32_e32 v33, v224
	s_add_u32 s4, s4, s34
	v_readlane_b32 s5, v252, 0
	s_addc_u32 s5, s5, 0
	v_add_u32_e32 v2, 0x200, v33
	v_add_u32_e32 v8, 0x400, v33
	v_add_u32_e32 v10, 0x600, v33
	s_lshl_b32 s46, s64, 2
	v_lshlrev_b32_e32 v0, 4, v33
	v_ashrrev_i32_e32 v34, 4, v33
	v_ashrrev_i32_e32 v36, 4, v2
	v_ashrrev_i32_e32 v38, 4, v8
	v_ashrrev_i32_e32 v40, 4, v10
	v_add_u32_e32 v16, 0x800, v33
	v_add_u32_e32 v18, 0xa00, v33
	s_add_u32 s46, s3, s46
	v_and_b32_e32 v192, 0xf0, v0
	v_add_u32_e32 v0, s2, v34
	v_add_u32_e32 v2, s2, v36
	v_add_u32_e32 v8, s2, v38
	v_add_u32_e32 v10, s2, v40
	v_ashrrev_i32_e32 v42, 4, v16
	v_ashrrev_i32_e32 v69, 4, v18
	v_add_u32_e32 v24, 0xc00, v33
	s_addc_u32 s47, s47, 0
	s_waitcnt lgkmcnt(0)
	v_ashrrev_i32_e32 v1, 31, v0
	v_ashrrev_i32_e32 v3, 31, v2
	v_ashrrev_i32_e32 v9, 31, v8
	v_ashrrev_i32_e32 v11, 31, v10
	v_add_u32_e32 v16, s2, v42
	v_add_u32_e32 v18, s2, v69
	v_ashrrev_i32_e32 v79, 4, v24
	v_add_u32_e32 v30, 0xe00, v33
	v_lshl_add_u64 v[28:29], s[46:47], 0, v[192:193]
	v_lshlrev_b64 v[0:1], 13, v[0:1]
	v_lshlrev_b64 v[2:3], 13, v[2:3]
	v_lshlrev_b64 v[8:9], 13, v[8:9]
	v_lshlrev_b64 v[10:11], 13, v[10:11]
	v_ashrrev_i32_e32 v17, 31, v16
	v_ashrrev_i32_e32 v19, 31, v18
	v_add_u32_e32 v24, s2, v79
	v_ashrrev_i32_e32 v80, 4, v30
	v_lshl_add_u64 v[0:1], v[28:29], 0, v[0:1]
	v_lshl_add_u64 v[4:5], v[28:29], 0, v[2:3]
	v_lshl_add_u64 v[8:9], v[28:29], 0, v[8:9]
	v_lshl_add_u64 v[12:13], v[28:29], 0, v[10:11]
	v_lshlrev_b64 v[16:17], 13, v[16:17]
	v_lshlrev_b64 v[18:19], 13, v[18:19]
	v_ashrrev_i32_e32 v25, 31, v24
	v_add_u32_e32 v30, s2, v80
	global_load_dwordx4 v[0:3], v[0:1], off nt
	s_nop 0
	global_load_dwordx4 v[4:7], v[4:5], off nt
	s_nop 0
	global_load_dwordx4 v[8:11], v[8:9], off nt
	s_nop 0
	global_load_dwordx4 v[12:15], v[12:13], off nt
	v_lshl_add_u64 v[16:17], v[28:29], 0, v[16:17]
	v_lshl_add_u64 v[20:21], v[28:29], 0, v[18:19]
	v_lshlrev_b64 v[24:25], 13, v[24:25]
	v_ashrrev_i32_e32 v31, 31, v30
	global_load_dwordx4 v[16:19], v[16:17], off nt
	s_nop 0
	global_load_dwordx4 v[20:23], v[20:21], off nt
	v_lshl_add_u64 v[24:25], v[28:29], 0, v[24:25]
	v_lshlrev_b64 v[30:31], 13, v[30:31]
	global_load_dwordx4 v[24:27], v[24:25], off nt
	v_lshl_add_u64 v[28:29], v[28:29], 0, v[30:31]
	global_load_dwordx4 v[28:31], v[28:29], off nt
	v_add_u32_e32 v32, 0, v192
	v_mad_u64_u32 v[34:35], s[46:47], v34, s97, v[32:33]
	v_mad_u64_u32 v[36:37], s[46:47], v36, s97, v[32:33]
	v_mad_u64_u32 v[38:39], s[46:47], v38, s97, v[32:33]
	v_mad_u64_u32 v[40:41], s[46:47], v40, s97, v[32:33]
	v_mad_u64_u32 v[42:43], s[46:47], v42, s97, v[32:33]
	s_ashr_i32 s3, s2, 31
	s_mov_b32 s9, 0xc000
	s_waitcnt vmcnt(0)
	ds_write2_b32 v34, v0, v1 offset1:1
	ds_write2_b32 v34, v2, v3 offset0:2 offset1:3
	ds_write2_b32 v36, v4, v5 offset1:1
	ds_write2_b32 v36, v6, v7 offset0:2 offset1:3
	ds_write2_b32 v38, v8, v9 offset1:1
	ds_write2_b32 v38, v10, v11 offset0:2 offset1:3
	ds_write2_b32 v40, v12, v13 offset1:1
	ds_write2_b32 v40, v14, v15 offset0:2 offset1:3
	ds_write2_b32 v42, v16, v17 offset1:1
	ds_write2_b32 v42, v18, v19 offset0:2 offset1:3
	v_mad_u64_u32 v[0:1], s[46:47], v69, s97, v[32:33]
	ds_write2_b32 v0, v20, v21 offset1:1
	ds_write2_b32 v0, v22, v23 offset0:2 offset1:3
	v_mad_u64_u32 v[0:1], s[46:47], v79, s97, v[32:33]
	ds_write2_b32 v0, v24, v25 offset1:1
	ds_write2_b32 v0, v26, v27 offset0:2 offset1:3
	v_mad_u64_u32 v[0:1], s[46:47], v80, s97, v[32:33]
	v_ashrrev_i32_e32 v2, 3, v33
	ds_write2_b32 v0, v28, v29 offset1:1
	ds_write2_b32 v0, v30, v31 offset0:2 offset1:3
	v_add_u32_e32 v0, s64, v2
	v_lshlrev_b32_e32 v3, 3, v33
	v_ashrrev_i32_e32 v1, 31, v0
	v_and_b32_e32 v3, 56, v3
	v_lshlrev_b32_e32 v2, 2, v2
	v_mul_u32_u24_e32 v4, 0x104, v3
	v_lshlrev_b64 v[0:1], 14, v[0:1]
	v_add3_u32 v32, 0, v2, v4
	v_lshl_add_u64 v[0:1], s[4:5], 0, v[0:1]
	v_lshl_add_u64 v[0:1], s[2:3], 1, v[0:1]
	v_lshlrev_b32_e32 v192, 1, v3
	v_add_u32_e32 v8, 0x400, v32
	s_waitcnt lgkmcnt(0)
	s_barrier
	v_lshl_add_u64 v[4:5], v[0:1], 0, v[192:193]
	ds_read2_b32 v[0:1], v32 offset1:65
	ds_read2_b32 v[2:3], v32 offset0:130 offset1:195
	ds_read2_b32 v[6:7], v8 offset0:4 offset1:69
	ds_read2_b32 v[8:9], v8 offset0:134 offset1:199
	v_add_u32_e32 v10, 0x4000, v32
	v_add_u32_e32 v12, 0x4200, v32
	v_add_u32_e32 v14, 0x4400, v32
	v_add_u32_e32 v16, 0x4600, v32
	v_add_u32_e32 v18, 0x8000, v32
	v_add_u32_e32 v22, 0x8400, v32
	ds_read2_b32 v[10:11], v10 offset0:64 offset1:129
	ds_read2_b32 v[12:13], v12 offset0:66 offset1:131
	ds_read2_b32 v[14:15], v14 offset0:68 offset1:133
	ds_read2_b32 v[16:17], v16 offset0:70 offset1:135
	ds_read2_b32 v[18:19], v18 offset0:128 offset1:193
	ds_read2_b32 v[20:21], v22 offset0:2 offset1:67
	ds_read2_b32 v[22:23], v22 offset0:132 offset1:197
	v_add_u32_e32 v24, 0x8800, v32
	v_add_u32_e32 v26, 0xc200, v32
	v_add_u32_e32 v28, 0xc400, v32
	v_add_u32_e32 v30, 0xc600, v32
	v_add_u32_e32 v32, 0xc800, v32
	ds_read2_b32 v[24:25], v24 offset0:6 offset1:71
	ds_read2_b32 v[26:27], v26 offset0:64 offset1:129
	ds_read2_b32 v[28:29], v28 offset0:66 offset1:131
	ds_read2_b32 v[30:31], v30 offset0:68 offset1:133
	ds_read2_b32 v[32:33], v32 offset0:70 offset1:135
	s_waitcnt lgkmcnt(14)
	v_cvt_pk_bf16_f32 v0, v0, v1
	v_cvt_pk_bf16_f32 v1, v2, v3
	s_waitcnt lgkmcnt(13)
	v_cvt_pk_bf16_f32 v2, v6, v7
	s_waitcnt lgkmcnt(12)
	v_cvt_pk_bf16_f32 v3, v8, v9
	global_store_dwordx4 v[4:5], v[0:3], off
	s_mov_b64 s[2:3], 0
	s_waitcnt lgkmcnt(11)
	v_cvt_pk_bf16_f32 v0, v10, v11
	s_waitcnt lgkmcnt(10)
	v_cvt_pk_bf16_f32 v1, v12, v13
	s_waitcnt lgkmcnt(9)
	v_cvt_pk_bf16_f32 v2, v14, v15
	s_waitcnt lgkmcnt(8)
	v_cvt_pk_bf16_f32 v3, v16, v17
	global_store_dwordx4 v[4:5], v[0:3], off offset:128
	s_waitcnt lgkmcnt(7)
	s_nop 0
	v_cvt_pk_bf16_f32 v0, v18, v19
	s_waitcnt lgkmcnt(6)
	v_cvt_pk_bf16_f32 v1, v20, v21
	s_waitcnt lgkmcnt(5)
	v_cvt_pk_bf16_f32 v2, v22, v23
	s_waitcnt lgkmcnt(4)
	v_cvt_pk_bf16_f32 v3, v24, v25
	global_store_dwordx4 v[4:5], v[0:3], off offset:256
	s_waitcnt lgkmcnt(3)
	s_nop 0
	v_cvt_pk_bf16_f32 v0, v26, v27
	s_waitcnt lgkmcnt(2)
	v_cvt_pk_bf16_f32 v1, v28, v29
	s_waitcnt lgkmcnt(1)
	v_cvt_pk_bf16_f32 v2, v30, v31
	s_waitcnt lgkmcnt(0)
	v_cvt_pk_bf16_f32 v3, v32, v33
	global_store_dwordx4 v[4:5], v[0:3], off offset:384
	s_barrier
.LBB0_619:
	s_andn2_b64 vcc, exec, s[2:3]
	s_cbranch_vccnz .LBB0_621
	s_add_u32 s4, s20, s35
	s_addc_u32 s5, s21, 0
	s_lshl_b32 s2, s28, 1
	s_and_b32 s2, s2, 0xf00
	s_add_i32 s64, s2, 0xfffffa00
	s_and_b32 s29, s29, 0x1fc0
	v_readlane_b32 s2, v252, 1
	v_mov_b32_e32 v33, v224
	s_add_u32 s2, s2, s34
	v_readlane_b32 s3, v252, 2
	s_addc_u32 s3, s3, 0
	v_add_u32_e32 v2, 0x200, v33
	v_add_u32_e32 v8, 0x400, v33
	v_add_u32_e32 v10, 0x600, v33
	s_lshl_b32 s34, s29, 2
	v_lshlrev_b32_e32 v0, 4, v33
	v_ashrrev_i32_e32 v34, 4, v33
	v_ashrrev_i32_e32 v36, 4, v2
	v_ashrrev_i32_e32 v38, 4, v8
	v_ashrrev_i32_e32 v40, 4, v10
	v_add_u32_e32 v16, 0x800, v33
	v_add_u32_e32 v18, 0xa00, v33
	s_add_u32 s4, s4, s34
	v_and_b32_e32 v192, 0xf0, v0
	v_add_u32_e32 v0, s64, v34
	v_add_u32_e32 v2, s64, v36
	v_add_u32_e32 v8, s64, v38
	v_add_u32_e32 v10, s64, v40
	v_ashrrev_i32_e32 v42, 4, v16
	v_ashrrev_i32_e32 v69, 4, v18
	v_add_u32_e32 v24, 0xc00, v33
	s_addc_u32 s5, s5, 0
	s_waitcnt lgkmcnt(0)
	v_ashrrev_i32_e32 v1, 31, v0
	v_ashrrev_i32_e32 v3, 31, v2
	v_ashrrev_i32_e32 v9, 31, v8
	v_ashrrev_i32_e32 v11, 31, v10
	v_add_u32_e32 v16, s64, v42
	v_add_u32_e32 v18, s64, v69
	v_ashrrev_i32_e32 v79, 4, v24
	v_add_u32_e32 v30, 0xe00, v33
	v_lshl_add_u64 v[28:29], s[4:5], 0, v[192:193]
	v_lshlrev_b64 v[0:1], 15, v[0:1]
	v_lshlrev_b64 v[2:3], 15, v[2:3]
	v_lshlrev_b64 v[8:9], 15, v[8:9]
	v_lshlrev_b64 v[10:11], 15, v[10:11]
	v_ashrrev_i32_e32 v17, 31, v16
	v_ashrrev_i32_e32 v19, 31, v18
	v_add_u32_e32 v24, s64, v79
	v_ashrrev_i32_e32 v80, 4, v30
	v_lshl_add_u64 v[0:1], v[28:29], 0, v[0:1]
	v_lshl_add_u64 v[4:5], v[28:29], 0, v[2:3]
	v_lshl_add_u64 v[8:9], v[28:29], 0, v[8:9]
	v_lshl_add_u64 v[12:13], v[28:29], 0, v[10:11]
	v_lshlrev_b64 v[16:17], 15, v[16:17]
	v_lshlrev_b64 v[18:19], 15, v[18:19]
	v_ashrrev_i32_e32 v25, 31, v24
	v_add_u32_e32 v30, s64, v80
	global_load_dwordx4 v[0:3], v[0:1], off nt
	s_nop 0
	global_load_dwordx4 v[4:7], v[4:5], off nt
	s_nop 0
	global_load_dwordx4 v[8:11], v[8:9], off nt
	s_nop 0
	global_load_dwordx4 v[12:15], v[12:13], off nt
	v_lshl_add_u64 v[16:17], v[28:29], 0, v[16:17]
	v_lshl_add_u64 v[20:21], v[28:29], 0, v[18:19]
	v_lshlrev_b64 v[24:25], 15, v[24:25]
	v_ashrrev_i32_e32 v31, 31, v30
	global_load_dwordx4 v[16:19], v[16:17], off nt
	s_nop 0
	global_load_dwordx4 v[20:23], v[20:21], off nt
	v_lshl_add_u64 v[24:25], v[28:29], 0, v[24:25]
	v_lshlrev_b64 v[30:31], 15, v[30:31]
	global_load_dwordx4 v[24:27], v[24:25], off nt
	v_lshl_add_u64 v[28:29], v[28:29], 0, v[30:31]
	global_load_dwordx4 v[28:31], v[28:29], off nt
	v_add_u32_e32 v32, 0, v192
	v_mad_u64_u32 v[34:35], s[4:5], v34, s97, v[32:33]
	v_mad_u64_u32 v[36:37], s[4:5], v36, s97, v[32:33]
	v_mad_u64_u32 v[38:39], s[4:5], v38, s97, v[32:33]
	v_mad_u64_u32 v[40:41], s[4:5], v40, s97, v[32:33]
	v_mad_u64_u32 v[42:43], s[4:5], v42, s97, v[32:33]
	s_waitcnt vmcnt(0)
	ds_write2_b32 v34, v0, v1 offset1:1
	ds_write2_b32 v34, v2, v3 offset0:2 offset1:3
	ds_write2_b32 v36, v4, v5 offset1:1
	ds_write2_b32 v36, v6, v7 offset0:2 offset1:3
	ds_write2_b32 v38, v8, v9 offset1:1
	ds_write2_b32 v38, v10, v11 offset0:2 offset1:3
	ds_write2_b32 v40, v12, v13 offset1:1
	ds_write2_b32 v40, v14, v15 offset0:2 offset1:3
	ds_write2_b32 v42, v16, v17 offset1:1
	ds_write2_b32 v42, v18, v19 offset0:2 offset1:3
	v_mad_u64_u32 v[0:1], s[4:5], v69, s97, v[32:33]
	ds_write2_b32 v0, v20, v21 offset1:1
	ds_write2_b32 v0, v22, v23 offset0:2 offset1:3
	v_mad_u64_u32 v[0:1], s[4:5], v79, s97, v[32:33]
	ds_write2_b32 v0, v24, v25 offset1:1
	ds_write2_b32 v0, v26, v27 offset0:2 offset1:3
	v_mad_u64_u32 v[0:1], s[4:5], v80, s97, v[32:33]
	v_ashrrev_i32_e32 v2, 3, v33
	ds_write2_b32 v0, v28, v29 offset1:1
	ds_write2_b32 v0, v30, v31 offset0:2 offset1:3
	v_add_u32_e32 v0, s29, v2
	v_lshlrev_b32_e32 v3, 3, v33
	v_ashrrev_i32_e32 v1, 31, v0
	v_and_b32_e32 v3, 56, v3
	v_lshlrev_b32_e32 v2, 2, v2
	v_mul_u32_u24_e32 v4, 0x104, v3
	v_lshlrev_b64 v[0:1], 12, v[0:1]
	v_add3_u32 v32, 0, v2, v4
	v_lshl_add_u64 v[0:1], s[2:3], 0, v[0:1]
	v_lshl_add_u64 v[0:1], s[64:65], 1, v[0:1]
	v_lshlrev_b32_e32 v192, 1, v3
	v_add_u32_e32 v8, 0x400, v32
	s_waitcnt lgkmcnt(0)
	s_barrier
	v_lshl_add_u64 v[4:5], v[0:1], 0, v[192:193]
	ds_read2_b32 v[0:1], v32 offset1:65
	ds_read2_b32 v[2:3], v32 offset0:130 offset1:195
	ds_read2_b32 v[6:7], v8 offset0:4 offset1:69
	ds_read2_b32 v[8:9], v8 offset0:134 offset1:199
	v_add_u32_e32 v10, 0x4000, v32
	v_add_u32_e32 v12, 0x4200, v32
	v_add_u32_e32 v14, 0x4400, v32
	v_add_u32_e32 v16, 0x4600, v32
	v_add_u32_e32 v18, 0x8000, v32
	v_add_u32_e32 v22, 0x8400, v32
	ds_read2_b32 v[10:11], v10 offset0:64 offset1:129
	ds_read2_b32 v[12:13], v12 offset0:66 offset1:131
	ds_read2_b32 v[14:15], v14 offset0:68 offset1:133
	ds_read2_b32 v[16:17], v16 offset0:70 offset1:135
	ds_read2_b32 v[18:19], v18 offset0:128 offset1:193
	ds_read2_b32 v[20:21], v22 offset0:2 offset1:67
	ds_read2_b32 v[22:23], v22 offset0:132 offset1:197
	v_add_u32_e32 v24, 0x8800, v32
	v_add_u32_e32 v26, 0xc200, v32
	v_add_u32_e32 v28, 0xc400, v32
	v_add_u32_e32 v30, 0xc600, v32
	v_add_u32_e32 v32, 0xc800, v32
	ds_read2_b32 v[24:25], v24 offset0:6 offset1:71
	ds_read2_b32 v[26:27], v26 offset0:64 offset1:129
	ds_read2_b32 v[28:29], v28 offset0:66 offset1:131
	ds_read2_b32 v[30:31], v30 offset0:68 offset1:133
	ds_read2_b32 v[32:33], v32 offset0:70 offset1:135
	s_waitcnt lgkmcnt(14)
	v_cvt_pk_bf16_f32 v0, v0, v1
	v_cvt_pk_bf16_f32 v1, v2, v3
	s_waitcnt lgkmcnt(13)
	v_cvt_pk_bf16_f32 v2, v6, v7
	s_waitcnt lgkmcnt(12)
	v_cvt_pk_bf16_f32 v3, v8, v9
	global_store_dwordx4 v[4:5], v[0:3], off
	s_waitcnt lgkmcnt(11)
	s_nop 0
	v_cvt_pk_bf16_f32 v0, v10, v11
	s_waitcnt lgkmcnt(10)
	v_cvt_pk_bf16_f32 v1, v12, v13
	s_waitcnt lgkmcnt(9)
	v_cvt_pk_bf16_f32 v2, v14, v15
	s_waitcnt lgkmcnt(8)
	v_cvt_pk_bf16_f32 v3, v16, v17
	global_store_dwordx4 v[4:5], v[0:3], off offset:128
	s_waitcnt lgkmcnt(7)
	s_nop 0
	v_cvt_pk_bf16_f32 v0, v18, v19
	s_waitcnt lgkmcnt(6)
	v_cvt_pk_bf16_f32 v1, v20, v21
	s_waitcnt lgkmcnt(5)
	v_cvt_pk_bf16_f32 v2, v22, v23
	s_waitcnt lgkmcnt(4)
	v_cvt_pk_bf16_f32 v3, v24, v25
	global_store_dwordx4 v[4:5], v[0:3], off offset:256
	s_waitcnt lgkmcnt(3)
	s_nop 0
	v_cvt_pk_bf16_f32 v0, v26, v27
	s_waitcnt lgkmcnt(2)
	v_cvt_pk_bf16_f32 v1, v28, v29
	s_waitcnt lgkmcnt(1)
	v_cvt_pk_bf16_f32 v2, v30, v31
	s_waitcnt lgkmcnt(0)
	v_cvt_pk_bf16_f32 v3, v32, v33
	global_store_dwordx4 v[4:5], v[0:3], off offset:384
	s_barrier

.LBB0_622:
	s_andn2_b64 vcc, exec, s[2:3]
	s_cbranch_vccnz .LBB0_628
	s_lshl_b32 s2, s28, 3
	s_and_b32 s29, s2, 0x1f00
	s_add_i32 s64, s29, 0xfffff000
	s_and_b32 s4, s28, 0x3c0
	s_and_b64 s[2:3], s[14:15], exec
	v_readlane_b32 s76, v253, 40
	s_cselect_b32 s2, 0x1000000, 0
	v_readlane_b32 s82, v253, 46
	v_readlane_b32 s83, v253, 47
	s_add_u32 s2, s82, s2
	s_addc_u32 s3, s83, 0
	s_lshl_b32 s5, s28, 6
	s_and_b32 s34, s5, 0x7c0
	s_lshl_b32 s5, s34, 2
	s_add_u32 s2, s2, s5
	s_addc_u32 s3, s3, 0
	s_cmpk_lg_i32 s4, 0x240
	s_mov_b64 s[4:5], -1
	v_readlane_b32 s77, v253, 41
	v_readlane_b32 s78, v253, 42
	v_readlane_b32 s79, v253, 43
	v_readlane_b32 s80, v253, 44
	v_readlane_b32 s81, v253, 45
	v_readlane_b32 s84, v253, 48
	v_readlane_b32 s85, v253, 49
	v_readlane_b32 s86, v253, 50
	v_readlane_b32 s87, v253, 51
	v_readlane_b32 s88, v253, 52
	v_readlane_b32 s89, v253, 53
	v_readlane_b32 s90, v253, 54
	v_readlane_b32 s91, v253, 55
	s_cbranch_scc0 .LBB0_625
	v_mov_b32_e32 v33, v224
	s_and_b64 s[4:5], s[14:15], exec
	v_add_u32_e32 v2, 0x200, v33
	v_add_u32_e32 v8, 0x400, v33
	v_add_u32_e32 v10, 0x600, v33
	v_add_u32_e32 v16, 0x800, v33
	v_add_u32_e32 v18, 0xa00, v33
	v_lshlrev_b32_e32 v0, 4, v33
	v_ashrrev_i32_e32 v34, 4, v33
	v_ashrrev_i32_e32 v36, 4, v2
	v_ashrrev_i32_e32 v38, 4, v8
	v_ashrrev_i32_e32 v40, 4, v10
	v_ashrrev_i32_e32 v42, 4, v16
	v_ashrrev_i32_e32 v69, 4, v18
	v_add_u32_e32 v24, 0xc00, v33
	v_and_b32_e32 v192, 0xf0, v0
	v_add_u32_e32 v0, s64, v34
	v_add_u32_e32 v2, s64, v36
	v_add_u32_e32 v8, s64, v38
	v_add_u32_e32 v10, s64, v40
	v_add_u32_e32 v16, s64, v42
	v_add_u32_e32 v18, s64, v69
	v_ashrrev_i32_e32 v79, 4, v24
	v_add_u32_e32 v30, 0xe00, v33
	s_waitcnt lgkmcnt(0)
	v_ashrrev_i32_e32 v1, 31, v0
	v_ashrrev_i32_e32 v3, 31, v2
	v_ashrrev_i32_e32 v9, 31, v8
	v_ashrrev_i32_e32 v11, 31, v10
	v_ashrrev_i32_e32 v17, 31, v16
	v_ashrrev_i32_e32 v19, 31, v18
	v_add_u32_e32 v24, s64, v79
	v_ashrrev_i32_e32 v96, 4, v30
	v_lshl_add_u64 v[28:29], s[2:3], 0, v[192:193]
	v_lshlrev_b64 v[0:1], 13, v[0:1]
	v_lshlrev_b64 v[2:3], 13, v[2:3]
	v_lshlrev_b64 v[8:9], 13, v[8:9]
	v_lshlrev_b64 v[10:11], 13, v[10:11]
	v_lshlrev_b64 v[16:17], 13, v[16:17]
	v_lshlrev_b64 v[18:19], 13, v[18:19]
	v_ashrrev_i32_e32 v25, 31, v24
	v_add_u32_e32 v30, s64, v96
	v_lshl_add_u64 v[0:1], v[28:29], 0, v[0:1]
	v_lshl_add_u64 v[4:5], v[28:29], 0, v[2:3]
	v_lshl_add_u64 v[8:9], v[28:29], 0, v[8:9]
	v_lshl_add_u64 v[12:13], v[28:29], 0, v[10:11]
	v_lshl_add_u64 v[16:17], v[28:29], 0, v[16:17]
	v_lshl_add_u64 v[20:21], v[28:29], 0, v[18:19]
	v_lshlrev_b64 v[24:25], 13, v[24:25]
	v_ashrrev_i32_e32 v31, 31, v30
	global_load_dwordx4 v[0:3], v[0:1], off nt
	s_nop 0
	global_load_dwordx4 v[4:7], v[4:5], off nt
	s_nop 0
	global_load_dwordx4 v[8:11], v[8:9], off nt
	s_nop 0
	global_load_dwordx4 v[12:15], v[12:13], off nt
	s_nop 0
	global_load_dwordx4 v[16:19], v[16:17], off nt
	s_nop 0
	global_load_dwordx4 v[20:23], v[20:21], off nt
	v_lshl_add_u64 v[24:25], v[28:29], 0, v[24:25]
	v_lshlrev_b64 v[30:31], 13, v[30:31]
	global_load_dwordx4 v[24:27], v[24:25], off nt
	v_lshl_add_u64 v[28:29], v[28:29], 0, v[30:31]
	global_load_dwordx4 v[28:31], v[28:29], off nt
	v_add_u32_e32 v32, 0, v192
	v_mad_u64_u32 v[34:35], s[46:47], v34, s97, v[32:33]
	v_mad_u64_u32 v[36:37], s[46:47], v36, s97, v[32:33]
	v_mad_u64_u32 v[38:39], s[46:47], v38, s97, v[32:33]
	v_mad_u64_u32 v[40:41], s[46:47], v40, s97, v[32:33]
	v_mad_u64_u32 v[42:43], s[46:47], v42, s97, v[32:33]
	v_mad_u64_u32 v[80:81], s[46:47], v69, s97, v[32:33]
	s_cselect_b32 s4, 0x800000, 0
	v_readlane_b32 s5, v252, 3
	s_add_u32 s4, s5, s4
	v_readlane_b32 s5, v252, 4
	s_addc_u32 s5, s5, 0
	s_mov_b32 s9, 0xc000
	s_waitcnt vmcnt(0)
	ds_write2_b32 v34, v0, v1 offset1:1
	ds_write2_b32 v34, v2, v3 offset0:2 offset1:3
	ds_write2_b32 v36, v4, v5 offset1:1
	ds_write2_b32 v36, v6, v7 offset0:2 offset1:3
	ds_write2_b32 v38, v8, v9 offset1:1
	ds_write2_b32 v38, v10, v11 offset0:2 offset1:3
	ds_write2_b32 v40, v12, v13 offset1:1
	ds_write2_b32 v40, v14, v15 offset0:2 offset1:3
	ds_write2_b32 v42, v16, v17 offset1:1
	ds_write2_b32 v42, v18, v19 offset0:2 offset1:3
	ds_write2_b32 v80, v20, v21 offset1:1
	ds_write2_b32 v80, v22, v23 offset0:2 offset1:3
	v_mad_u64_u32 v[0:1], s[46:47], v79, s97, v[32:33]
	ds_write2_b32 v0, v24, v25 offset1:1
	ds_write2_b32 v0, v26, v27 offset0:2 offset1:3
	v_mad_u64_u32 v[0:1], s[46:47], v96, s97, v[32:33]
	v_ashrrev_i32_e32 v2, 3, v33
	ds_write2_b32 v0, v28, v29 offset1:1
	ds_write2_b32 v0, v30, v31 offset0:2 offset1:3
	v_add_u32_e32 v0, s34, v2
	v_lshlrev_b32_e32 v3, 3, v33
	v_ashrrev_i32_e32 v1, 31, v0
	v_and_b32_e32 v3, 56, v3
	v_lshlrev_b32_e32 v2, 2, v2
	v_mul_u32_u24_e32 v4, 0x104, v3
	v_lshlrev_b64 v[0:1], 12, v[0:1]
	v_add3_u32 v32, 0, v2, v4
	v_lshl_add_u64 v[0:1], s[4:5], 0, v[0:1]
	v_lshl_add_u64 v[0:1], s[64:65], 1, v[0:1]
	v_lshlrev_b32_e32 v192, 1, v3
	v_add_u32_e32 v8, 0x400, v32
	s_waitcnt lgkmcnt(0)
	s_barrier
	v_lshl_add_u64 v[4:5], v[0:1], 0, v[192:193]
	ds_read2_b32 v[0:1], v32 offset1:65
	ds_read2_b32 v[2:3], v32 offset0:130 offset1:195
	ds_read2_b32 v[6:7], v8 offset0:4 offset1:69
	ds_read2_b32 v[8:9], v8 offset0:134 offset1:199
	v_add_u32_e32 v10, 0x4000, v32
	v_add_u32_e32 v12, 0x4200, v32
	v_add_u32_e32 v14, 0x4400, v32
	v_add_u32_e32 v16, 0x4600, v32
	v_add_u32_e32 v18, 0x8000, v32
	v_add_u32_e32 v22, 0x8400, v32
	ds_read2_b32 v[10:11], v10 offset0:64 offset1:129
	ds_read2_b32 v[12:13], v12 offset0:66 offset1:131
	ds_read2_b32 v[14:15], v14 offset0:68 offset1:133
	ds_read2_b32 v[16:17], v16 offset0:70 offset1:135
	ds_read2_b32 v[18:19], v18 offset0:128 offset1:193
	ds_read2_b32 v[20:21], v22 offset0:2 offset1:67
	ds_read2_b32 v[22:23], v22 offset0:132 offset1:197
	v_add_u32_e32 v24, 0x8800, v32
	v_add_u32_e32 v26, 0xc200, v32
	v_add_u32_e32 v28, 0xc400, v32
	v_add_u32_e32 v30, 0xc600, v32
	v_add_u32_e32 v32, 0xc800, v32
	ds_read2_b32 v[24:25], v24 offset0:6 offset1:71
	ds_read2_b32 v[26:27], v26 offset0:64 offset1:129
	ds_read2_b32 v[28:29], v28 offset0:66 offset1:131
	ds_read2_b32 v[30:31], v30 offset0:68 offset1:133
	ds_read2_b32 v[32:33], v32 offset0:70 offset1:135
	s_waitcnt lgkmcnt(14)
	v_cvt_pk_bf16_f32 v0, v0, v1
	v_cvt_pk_bf16_f32 v1, v2, v3
	s_waitcnt lgkmcnt(13)
	v_cvt_pk_bf16_f32 v2, v6, v7
	s_waitcnt lgkmcnt(12)
	v_cvt_pk_bf16_f32 v3, v8, v9
	global_store_dwordx4 v[4:5], v[0:3], off
	s_mov_b64 s[4:5], 0
	s_waitcnt lgkmcnt(11)
	v_cvt_pk_bf16_f32 v0, v10, v11
	s_waitcnt lgkmcnt(10)
	v_cvt_pk_bf16_f32 v1, v12, v13
	s_waitcnt lgkmcnt(9)
	v_cvt_pk_bf16_f32 v2, v14, v15
	s_waitcnt lgkmcnt(8)
	v_cvt_pk_bf16_f32 v3, v16, v17
	global_store_dwordx4 v[4:5], v[0:3], off offset:128
	s_waitcnt lgkmcnt(7)
	s_nop 0
	v_cvt_pk_bf16_f32 v0, v18, v19
	s_waitcnt lgkmcnt(6)
	v_cvt_pk_bf16_f32 v1, v20, v21
	s_waitcnt lgkmcnt(5)
	v_cvt_pk_bf16_f32 v2, v22, v23
	s_waitcnt lgkmcnt(4)
	v_cvt_pk_bf16_f32 v3, v24, v25
	global_store_dwordx4 v[4:5], v[0:3], off offset:256
	s_waitcnt lgkmcnt(3)
	s_nop 0
	v_cvt_pk_bf16_f32 v0, v26, v27
	s_waitcnt lgkmcnt(2)
	v_cvt_pk_bf16_f32 v1, v28, v29
	s_waitcnt lgkmcnt(1)
	v_cvt_pk_bf16_f32 v2, v30, v31
	s_waitcnt lgkmcnt(0)
	v_cvt_pk_bf16_f32 v3, v32, v33
	global_store_dwordx4 v[4:5], v[0:3], off offset:384
	s_barrier
.LBB0_625:
	s_andn2_b64 vcc, exec, s[4:5]
	s_cbranch_vccnz .LBB0_627
	v_mov_b32_e32 v33, v224
	s_nop 0
	v_add_u32_e32 v2, 0x200, v33
	v_add_u32_e32 v8, 0x400, v33
	v_add_u32_e32 v10, 0x600, v33
	v_add_u32_e32 v16, 0x800, v33
	v_add_u32_e32 v18, 0xa00, v33
	v_lshlrev_b32_e32 v0, 4, v33
	v_ashrrev_i32_e32 v34, 4, v33
	v_ashrrev_i32_e32 v36, 4, v2
	v_ashrrev_i32_e32 v38, 4, v8
	v_ashrrev_i32_e32 v40, 4, v10
	v_ashrrev_i32_e32 v42, 4, v16
	v_ashrrev_i32_e32 v69, 4, v18
	v_add_u32_e32 v24, 0xc00, v33
	v_and_b32_e32 v192, 0xf0, v0
	v_add_u32_e32 v0, s64, v34
	v_add_u32_e32 v2, s64, v36
	v_add_u32_e32 v8, s64, v38
	v_add_u32_e32 v10, s64, v40
	v_add_u32_e32 v16, s64, v42
	v_add_u32_e32 v18, s64, v69
	v_ashrrev_i32_e32 v79, 4, v24
	v_add_u32_e32 v30, 0xe00, v33
	s_waitcnt lgkmcnt(0)
	v_ashrrev_i32_e32 v1, 31, v0
	v_ashrrev_i32_e32 v3, 31, v2
	v_ashrrev_i32_e32 v9, 31, v8
	v_ashrrev_i32_e32 v11, 31, v10
	v_ashrrev_i32_e32 v17, 31, v16
	v_ashrrev_i32_e32 v19, 31, v18
	v_add_u32_e32 v24, s64, v79
	v_ashrrev_i32_e32 v96, 4, v30
	v_lshl_add_u64 v[28:29], s[2:3], 0, v[192:193]
	v_lshlrev_b64 v[0:1], 13, v[0:1]
	v_lshlrev_b64 v[2:3], 13, v[2:3]
	v_lshlrev_b64 v[8:9], 13, v[8:9]
	v_lshlrev_b64 v[10:11], 13, v[10:11]
	v_lshlrev_b64 v[16:17], 13, v[16:17]
	v_lshlrev_b64 v[18:19], 13, v[18:19]
	v_ashrrev_i32_e32 v25, 31, v24
	v_add_u32_e32 v30, s64, v96
	v_lshl_add_u64 v[0:1], v[28:29], 0, v[0:1]
	v_lshl_add_u64 v[4:5], v[28:29], 0, v[2:3]
	v_lshl_add_u64 v[8:9], v[28:29], 0, v[8:9]
	v_lshl_add_u64 v[12:13], v[28:29], 0, v[10:11]
	v_lshl_add_u64 v[16:17], v[28:29], 0, v[16:17]
	v_lshl_add_u64 v[20:21], v[28:29], 0, v[18:19]
	v_lshlrev_b64 v[24:25], 13, v[24:25]
	v_ashrrev_i32_e32 v31, 31, v30
	global_load_dwordx4 v[0:3], v[0:1], off nt
	s_nop 0
	global_load_dwordx4 v[4:7], v[4:5], off nt
	s_nop 0
	global_load_dwordx4 v[8:11], v[8:9], off nt
	s_nop 0
	global_load_dwordx4 v[12:15], v[12:13], off nt
	s_nop 0
	global_load_dwordx4 v[16:19], v[16:17], off nt
	s_nop 0
	global_load_dwordx4 v[20:23], v[20:21], off nt
	v_lshl_add_u64 v[24:25], v[28:29], 0, v[24:25]
	v_lshlrev_b64 v[30:31], 13, v[30:31]
	global_load_dwordx4 v[24:27], v[24:25], off nt
	v_lshl_add_u64 v[28:29], v[28:29], 0, v[30:31]
	global_load_dwordx4 v[28:31], v[28:29], off nt
	v_add_u32_e32 v32, 0, v192
	v_mad_u64_u32 v[34:35], s[4:5], v34, s97, v[32:33]
	v_mad_u64_u32 v[36:37], s[4:5], v36, s97, v[32:33]
	v_mad_u64_u32 v[38:39], s[4:5], v38, s97, v[32:33]
	v_mad_u64_u32 v[40:41], s[4:5], v40, s97, v[32:33]
	v_mad_u64_u32 v[42:43], s[4:5], v42, s97, v[32:33]
	v_mad_u64_u32 v[80:81], s[4:5], v69, s97, v[32:33]
	s_and_b64 s[2:3], s[14:15], exec
	s_cselect_b32 s2, 0x200000, 0
	s_add_u32 s2, s26, s2
	s_addc_u32 s3, s27, 0
	s_lshl_b32 s64, s29, 1
	s_waitcnt vmcnt(0)
	ds_write2_b32 v34, v0, v1 offset1:1
	ds_write2_b32 v34, v2, v3 offset0:2 offset1:3
	ds_write2_b32 v36, v4, v5 offset1:1
	ds_write2_b32 v36, v6, v7 offset0:2 offset1:3
	ds_write2_b32 v38, v8, v9 offset1:1
	ds_write2_b32 v38, v10, v11 offset0:2 offset1:3
	ds_write2_b32 v40, v12, v13 offset1:1
	ds_write2_b32 v40, v14, v15 offset0:2 offset1:3
	ds_write2_b32 v42, v16, v17 offset1:1
	ds_write2_b32 v42, v18, v19 offset0:2 offset1:3
	ds_write2_b32 v80, v20, v21 offset1:1
	ds_write2_b32 v80, v22, v23 offset0:2 offset1:3
	v_mad_u64_u32 v[0:1], s[4:5], v79, s97, v[32:33]
	ds_write2_b32 v0, v24, v25 offset1:1
	ds_write2_b32 v0, v26, v27 offset0:2 offset1:3
	v_mad_u64_u32 v[0:1], s[4:5], v96, s97, v[32:33]
	v_ashrrev_i32_e32 v2, 3, v33
	ds_write2_b32 v0, v28, v29 offset1:1
	ds_write2_b32 v0, v30, v31 offset0:2 offset1:3
	v_add_u32_e32 v0, s34, v2
	v_lshlrev_b32_e32 v3, 3, v33
	v_ashrrev_i32_e32 v1, 31, v0
	v_and_b32_e32 v3, 56, v3
	v_lshlrev_b32_e32 v2, 2, v2
	v_mul_u32_u24_e32 v4, 0x104, v3
	v_lshlrev_b64 v[0:1], 10, v[0:1]
	v_add3_u32 v34, 0, v2, v4
	v_lshl_add_u64 v[0:1], s[2:3], 0, v[0:1]
	v_lshl_add_u64 v[0:1], v[0:1], 0, s[64:65]
	v_lshlrev_b32_e32 v192, 1, v3
	v_add_u32_e32 v10, 0x400, v34
	s_waitcnt lgkmcnt(0)
	s_barrier
	v_lshl_add_u64 v[4:5], v[0:1], 0, v[192:193]
	ds_read2_b32 v[0:1], v34 offset1:65
	ds_read2_b32 v[2:3], v34 offset0:130 offset1:195
	ds_read2_b32 v[8:9], v10 offset0:4 offset1:69
	ds_read2_b32 v[10:11], v10 offset0:134 offset1:199
	v_add_u32_e32 v12, 0x4000, v34
	v_add_u32_e32 v14, 0x4200, v34
	v_add_u32_e32 v16, 0x4400, v34
	v_add_u32_e32 v18, 0x4600, v34
	v_add_u32_e32 v20, 0x8000, v34
	v_add_u32_e32 v24, 0x8400, v34
	s_mov_b64 s[2:3], 0x3dfdc00
	ds_read2_b32 v[12:13], v12 offset0:64 offset1:129
	ds_read2_b32 v[14:15], v14 offset0:66 offset1:131
	ds_read2_b32 v[16:17], v16 offset0:68 offset1:133
	ds_read2_b32 v[18:19], v18 offset0:70 offset1:135
	ds_read2_b32 v[20:21], v20 offset0:128 offset1:193
	ds_read2_b32 v[22:23], v24 offset0:2 offset1:67
	ds_read2_b32 v[24:25], v24 offset0:132 offset1:197
	v_lshl_add_u64 v[6:7], v[4:5], 0, s[2:3]
	s_mov_b32 s2, 0x3dfd000
	v_add_u32_e32 v26, 0x8800, v34
	v_add_u32_e32 v28, 0xc200, v34
	v_add_u32_e32 v30, 0xc400, v34
	v_add_u32_e32 v32, 0xc600, v34
	v_add_u32_e32 v34, 0xc800, v34
	v_add_co_u32_e32 v4, vcc, s2, v4
	ds_read2_b32 v[26:27], v26 offset0:6 offset1:71
	ds_read2_b32 v[28:29], v28 offset0:64 offset1:129
	ds_read2_b32 v[30:31], v30 offset0:66 offset1:131
	ds_read2_b32 v[32:33], v32 offset0:68 offset1:133
	ds_read2_b32 v[34:35], v34 offset0:70 offset1:135
	s_waitcnt lgkmcnt(14)
	v_cvt_pk_bf16_f32 v0, v0, v1
	v_cvt_pk_bf16_f32 v1, v2, v3
	s_waitcnt lgkmcnt(13)
	v_cvt_pk_bf16_f32 v2, v8, v9
	s_waitcnt lgkmcnt(12)
	v_cvt_pk_bf16_f32 v3, v10, v11
	v_addc_co_u32_e32 v5, vcc, 0, v5, vcc
	global_store_dwordx4 v[4:5], v[0:3], off offset:3072
	s_waitcnt lgkmcnt(11)
	s_nop 0
	v_cvt_pk_bf16_f32 v0, v12, v13
	s_waitcnt lgkmcnt(10)
	v_cvt_pk_bf16_f32 v1, v14, v15
	s_waitcnt lgkmcnt(9)
	v_cvt_pk_bf16_f32 v2, v16, v17
	s_waitcnt lgkmcnt(8)
	v_cvt_pk_bf16_f32 v3, v18, v19
	global_store_dwordx4 v[6:7], v[0:3], off offset:128
	s_waitcnt lgkmcnt(7)
	s_nop 0
	v_cvt_pk_bf16_f32 v0, v20, v21
	s_waitcnt lgkmcnt(6)
	v_cvt_pk_bf16_f32 v1, v22, v23
	s_waitcnt lgkmcnt(5)
	v_cvt_pk_bf16_f32 v2, v24, v25
	s_waitcnt lgkmcnt(4)
	v_cvt_pk_bf16_f32 v3, v26, v27
	global_store_dwordx4 v[6:7], v[0:3], off offset:256
	s_waitcnt lgkmcnt(3)
	s_nop 0
	v_cvt_pk_bf16_f32 v0, v28, v29
	s_waitcnt lgkmcnt(2)
	v_cvt_pk_bf16_f32 v1, v30, v31
	s_waitcnt lgkmcnt(1)
	v_cvt_pk_bf16_f32 v2, v32, v33
	s_waitcnt lgkmcnt(0)
	v_cvt_pk_bf16_f32 v3, v34, v35
	global_store_dwordx4 v[6:7], v[0:3], off offset:384
	s_barrier

.LBB0_629:
	s_andn2_b64 vcc, exec, s[2:3]
	s_cbranch_vccnz .LBB0_639
	s_and_b64 s[2:3], s[14:15], exec
	v_readlane_b32 s76, v253, 40
	s_cselect_b32 s2, 0x2400000, 0
	v_readlane_b32 s80, v253, 44
	v_readlane_b32 s81, v253, 45
	s_add_u32 s2, s80, s2
	s_addc_u32 s3, s81, 0
	s_lshl_b32 s4, s28, 2
	s_and_b32 s29, s4, 0x700
	s_lshl_b32 s4, s28, 6
	s_and_b32 s28, s4, 0xfc0
	s_add_i32 s4, s28, 0x200
	v_mov_b32_e32 v2, v224
	s_lshl_b32 s5, s28, 2
	s_add_u32 s2, s2, s5
	v_lshlrev_b32_e32 v0, 4, v2
	v_add_u32_e32 v6, 0x200, v2
	v_add_u32_e32 v12, 0x400, v2
	v_add_u32_e32 v14, 0x600, v2
	v_add_u32_e32 v20, 0x800, v2
	v_add_u32_e32 v22, 0xa00, v2
	v_add_u32_e32 v28, 0xc00, v2
	v_add_u32_e32 v32, 0xe00, v2
	s_addc_u32 s3, s3, 0
	v_and_b32_e32 v192, 0xf0, v0
	s_waitcnt lgkmcnt(0)
	v_ashrrev_i32_e32 v3, 4, v2
	v_ashrrev_i32_e32 v38, 4, v6
	v_ashrrev_i32_e32 v40, 4, v12
	v_ashrrev_i32_e32 v42, 4, v14
	v_ashrrev_i32_e32 v69, 4, v20
	v_ashrrev_i32_e32 v79, 4, v22
	v_ashrrev_i32_e32 v98, 4, v28
	v_ashrrev_i32_e32 v100, 4, v32
	v_lshl_add_u64 v[0:1], s[2:3], 0, v[192:193]
	v_add_u32_e32 v4, s29, v3
	s_movk_i32 s5, 0x4800
	v_add_u32_e32 v6, s29, v38
	v_add_u32_e32 v12, s29, v40
	v_add_u32_e32 v14, s29, v42
	v_add_u32_e32 v20, s29, v69
	v_add_u32_e32 v22, s29, v79
	v_add_u32_e32 v28, s29, v98
	v_add_u32_e32 v32, s29, v100
	v_mad_i64_i32 v[4:5], s[2:3], v4, s5, v[0:1]
	v_mad_i64_i32 v[8:9], s[2:3], v6, s5, v[0:1]
	v_mad_i64_i32 v[12:13], s[2:3], v12, s5, v[0:1]
	v_mad_i64_i32 v[16:17], s[2:3], v14, s5, v[0:1]
	v_mad_i64_i32 v[20:21], s[2:3], v20, s5, v[0:1]
	v_mad_i64_i32 v[24:25], s[2:3], v22, s5, v[0:1]
	v_mad_i64_i32 v[28:29], s[2:3], v28, s5, v[0:1]
	v_mad_i64_i32 v[0:1], s[2:3], v32, s5, v[0:1]
	global_load_dwordx4 v[4:7], v[4:5], off offset:2048 nt
	s_nop 0
	global_load_dwordx4 v[8:11], v[8:9], off offset:2048 nt
	s_nop 0
	global_load_dwordx4 v[12:15], v[12:13], off offset:2048 nt
	s_nop 0
	global_load_dwordx4 v[16:19], v[16:17], off offset:2048 nt
	s_nop 0
	global_load_dwordx4 v[20:23], v[20:21], off offset:2048 nt
	s_nop 0
	global_load_dwordx4 v[24:27], v[24:25], off offset:2048 nt
	v_readlane_b32 s77, v253, 41
	global_load_dwordx4 v[28:31], v[28:29], off offset:2048 nt
	v_readlane_b32 s78, v253, 42
	global_load_dwordx4 v[32:35], v[0:1], off offset:2048 nt
	v_add_u32_e32 v0, 0, v192
	v_mad_u64_u32 v[36:37], s[2:3], v3, s97, v[0:1]
	v_mad_u64_u32 v[38:39], s[2:3], v38, s97, v[0:1]
	v_mad_u64_u32 v[40:41], s[2:3], v40, s97, v[0:1]
	v_mad_u64_u32 v[42:43], s[2:3], v42, s97, v[0:1]
	v_mad_u64_u32 v[80:81], s[2:3], v69, s97, v[0:1]
	v_mad_u64_u32 v[96:97], s[2:3], v79, s97, v[0:1]
	v_mad_u64_u32 v[98:99], s[2:3], v98, s97, v[0:1]
	v_mad_u64_u32 v[0:1], s[2:3], v100, s97, v[0:1]
	v_ashrrev_i32_e32 v3, 3, v2
	v_add_u32_e32 v1, s4, v3
	s_movk_i32 s2, 0x5ff
	v_cmp_lt_i32_e32 vcc, s2, v1
	v_readlane_b32 s79, v253, 43
	v_readlane_b32 s82, v253, 46
	v_readlane_b32 s83, v253, 47
	v_readlane_b32 s84, v253, 48
	v_readlane_b32 s85, v253, 49
	v_readlane_b32 s86, v253, 50
	v_readlane_b32 s87, v253, 51
	v_readlane_b32 s88, v253, 52
	v_readlane_b32 s89, v253, 53
	v_readlane_b32 s90, v253, 54
	v_readlane_b32 s91, v253, 55
	s_waitcnt vmcnt(0)
	ds_write2_b32 v36, v4, v5 offset1:1
	ds_write2_b32 v36, v6, v7 offset0:2 offset1:3
	ds_write2_b32 v38, v8, v9 offset1:1
	ds_write2_b32 v38, v10, v11 offset0:2 offset1:3
	ds_write2_b32 v40, v12, v13 offset1:1
	ds_write2_b32 v40, v14, v15 offset0:2 offset1:3
	ds_write2_b32 v42, v16, v17 offset1:1
	ds_write2_b32 v42, v18, v19 offset0:2 offset1:3
	ds_write2_b32 v80, v20, v21 offset1:1
	ds_write2_b32 v80, v22, v23 offset0:2 offset1:3
	ds_write2_b32 v96, v24, v25 offset1:1
	ds_write2_b32 v96, v26, v27 offset0:2 offset1:3
	ds_write2_b32 v98, v28, v29 offset1:1
	ds_write2_b32 v98, v30, v31 offset0:2 offset1:3
	ds_write2_b32 v0, v32, v33 offset1:1
	ds_write2_b32 v0, v34, v35 offset0:2 offset1:3
	s_waitcnt lgkmcnt(0)
	s_barrier
	s_and_saveexec_b64 s[2:3], vcc
	s_xor_b64 s[2:3], exec, s[2:3]
	s_cbranch_execz .LBB0_636
	s_movk_i32 s4, 0xdff
	v_cmp_lt_u32_e32 vcc, s4, v1
	s_and_saveexec_b64 s[4:5], vcc
	s_xor_b64 s[4:5], exec, s[4:5]
	v_add_u32_e32 v0, 0xfffff600, v1
	s_andn2_saveexec_b64 s[4:5], s[4:5]
	v_lshlrev_b32_e32 v0, 1, v1
	v_and_b32_e32 v0, 56, v0
	s_movk_i32 s34, 0xfc0
	v_and_or_b32 v0, v1, s34, v0
	v_lshrrev_b32_e32 v1, 3, v3
	v_and_b32_e32 v1, 4, v1
	v_bfe_u32 v4, v2, 3, 2
	v_or3_b32 v0, v0, v1, v4
	v_add_u32_e32 v0, 0x600, v0
	s_or_b64 exec, exec, s[4:5]

.LBB0_645:
	s_mov_b32 s3, 0x300000
	v_add_co_u32_e32 v20, vcc, s3, v80
	global_load_dwordx4 v[96:99], v[80:81], off nt
	s_nop 0
	v_addc_co_u32_e32 v21, vcc, 0, v81, vcc
	global_load_dwordx4 v[100:103], v[20:21], off nt
	s_mov_b32 s3, 0x600000
	v_add_co_u32_e32 v20, vcc, s3, v80
	s_mov_b32 s3, 0x900000
	s_nop 0
	v_addc_co_u32_e32 v21, vcc, 0, v81, vcc
	global_load_dwordx4 v[40:43], v[20:21], off nt
	v_add_co_u32_e32 v20, vcc, s3, v80
	s_mov_b32 s3, 0xf00000
	s_nop 0
	v_addc_co_u32_e32 v21, vcc, 0, v81, vcc
	global_load_dwordx4 v[36:39], v[20:21], off nt
	v_add_co_u32_e32 v20, vcc, s43, v80
	ds_read2st64_b32 v[104:105], v69 offset1:1
	ds_read2st64_b32 v[106:107], v69 offset0:32 offset1:33
	ds_read2st64_b32 v[108:109], v69 offset0:64 offset1:65
	ds_read2st64_b32 v[110:111], v69 offset0:96 offset1:97
	v_addc_co_u32_e32 v21, vcc, 0, v81, vcc
	global_load_dwordx4 v[32:35], v[20:21], off nt
	v_add_co_u32_e32 v20, vcc, s3, v80
	s_mov_b32 s3, 0x1200000
	s_nop 0
	v_addc_co_u32_e32 v21, vcc, 0, v81, vcc
	global_load_dwordx4 v[28:31], v[20:21], off nt
	v_add_co_u32_e32 v20, vcc, s3, v80
	s_mov_b32 s3, 0x1500000
	s_nop 0
	v_addc_co_u32_e32 v21, vcc, 0, v81, vcc
	global_load_dwordx4 v[24:27], v[20:21], off nt
	v_add_co_u32_e32 v20, vcc, s3, v80
	ds_read2st64_b32 v[112:113], v69 offset0:128 offset1:129
	s_nop 0
	v_addc_co_u32_e32 v21, vcc, 0, v81, vcc
	global_load_dwordx4 v[20:23], v[20:21], off nt
	s_mov_b64 s[14:15], 0x1800000
	s_add_i32 s2, s2, 8
	v_lshl_add_u64 v[80:81], v[80:81], 0, s[14:15]
	s_cmp_gt_u32 s2, 23
	s_waitcnt vmcnt(7) lgkmcnt(4)
	v_pk_fma_f32 v[2:3], v[98:99], v[104:105], v[2:3] op_sel_hi:[1,0,1]
	v_pk_fma_f32 v[0:1], v[96:97], v[104:105], v[0:1] op_sel_hi:[1,0,1]
	s_waitcnt lgkmcnt(3)
	v_pk_fma_f32 v[4:5], v[96:97], v[106:107], v[4:5] op_sel_hi:[1,0,1]
	s_waitcnt lgkmcnt(2)
	v_pk_fma_f32 v[8:9], v[96:97], v[108:109], v[8:9] op_sel_hi:[1,0,1]
	s_waitcnt lgkmcnt(1)
	v_pk_fma_f32 v[12:13], v[96:97], v[110:111], v[12:13] op_sel_hi:[1,0,1]
	s_waitcnt lgkmcnt(0)
	v_pk_fma_f32 v[16:17], v[96:97], v[112:113], v[16:17] op_sel_hi:[1,0,1]
	v_mov_b32_e32 v96, v105
	v_pk_fma_f32 v[6:7], v[98:99], v[106:107], v[6:7] op_sel_hi:[1,0,1]
	s_waitcnt vmcnt(6)
	v_pk_fma_f32 v[2:3], v[102:103], v[96:97], v[2:3] op_sel_hi:[1,0,1]
	v_pk_fma_f32 v[0:1], v[100:101], v[96:97], v[0:1] op_sel_hi:[1,0,1]
	v_mov_b32_e32 v96, v107
	v_pk_fma_f32 v[10:11], v[98:99], v[108:109], v[10:11] op_sel_hi:[1,0,1]
	v_pk_fma_f32 v[6:7], v[102:103], v[96:97], v[6:7] op_sel_hi:[1,0,1]
	v_pk_fma_f32 v[4:5], v[100:101], v[96:97], v[4:5] op_sel_hi:[1,0,1]
	v_mov_b32_e32 v96, v109
	v_pk_fma_f32 v[14:15], v[98:99], v[110:111], v[14:15] op_sel_hi:[1,0,1]
	v_pk_fma_f32 v[10:11], v[102:103], v[96:97], v[10:11] op_sel_hi:[1,0,1]
	v_pk_fma_f32 v[8:9], v[100:101], v[96:97], v[8:9] op_sel_hi:[1,0,1]
	v_mov_b32_e32 v96, v111
	v_pk_fma_f32 v[18:19], v[98:99], v[112:113], v[18:19] op_sel_hi:[1,0,1]
	v_pk_fma_f32 v[14:15], v[102:103], v[96:97], v[14:15] op_sel_hi:[1,0,1]
	v_pk_fma_f32 v[12:13], v[100:101], v[96:97], v[12:13] op_sel_hi:[1,0,1]
	v_mov_b32_e32 v96, v113
	v_pk_fma_f32 v[18:19], v[102:103], v[96:97], v[18:19] op_sel_hi:[1,0,1]
	v_pk_fma_f32 v[16:17], v[100:101], v[96:97], v[16:17] op_sel_hi:[1,0,1]
	ds_read2st64_b32 v[96:97], v69 offset0:2 offset1:3
	ds_read2st64_b32 v[98:99], v69 offset0:34 offset1:35
	ds_read2st64_b32 v[100:101], v69 offset0:66 offset1:67
	ds_read2st64_b32 v[102:103], v69 offset0:98 offset1:99
	ds_read2st64_b32 v[104:105], v69 offset0:130 offset1:131
	s_waitcnt vmcnt(5) lgkmcnt(4)
	v_pk_fma_f32 v[2:3], v[42:43], v[96:97], v[2:3] op_sel_hi:[1,0,1]
	v_pk_fma_f32 v[0:1], v[40:41], v[96:97], v[0:1] op_sel_hi:[1,0,1]
	s_waitcnt lgkmcnt(3)
	v_pk_fma_f32 v[4:5], v[40:41], v[98:99], v[4:5] op_sel_hi:[1,0,1]
	s_waitcnt lgkmcnt(2)
	v_pk_fma_f32 v[8:9], v[40:41], v[100:101], v[8:9] op_sel_hi:[1,0,1]
	s_waitcnt lgkmcnt(1)
	v_pk_fma_f32 v[12:13], v[40:41], v[102:103], v[12:13] op_sel_hi:[1,0,1]
	s_waitcnt lgkmcnt(0)
	v_pk_fma_f32 v[16:17], v[40:41], v[104:105], v[16:17] op_sel_hi:[1,0,1]
	v_mov_b32_e32 v40, v97
	v_pk_fma_f32 v[6:7], v[42:43], v[98:99], v[6:7] op_sel_hi:[1,0,1]
	s_waitcnt vmcnt(4)
	v_pk_fma_f32 v[2:3], v[38:39], v[40:41], v[2:3] op_sel_hi:[1,0,1]
	v_pk_fma_f32 v[0:1], v[36:37], v[40:41], v[0:1] op_sel_hi:[1,0,1]
	v_mov_b32_e32 v40, v99
	v_pk_fma_f32 v[10:11], v[42:43], v[100:101], v[10:11] op_sel_hi:[1,0,1]
	v_pk_fma_f32 v[6:7], v[38:39], v[40:41], v[6:7] op_sel_hi:[1,0,1]
	v_pk_fma_f32 v[4:5], v[36:37], v[40:41], v[4:5] op_sel_hi:[1,0,1]
	v_mov_b32_e32 v40, v101
	v_pk_fma_f32 v[14:15], v[42:43], v[102:103], v[14:15] op_sel_hi:[1,0,1]
	v_pk_fma_f32 v[10:11], v[38:39], v[40:41], v[10:11] op_sel_hi:[1,0,1]
	v_pk_fma_f32 v[8:9], v[36:37], v[40:41], v[8:9] op_sel_hi:[1,0,1]
	v_mov_b32_e32 v40, v103
	v_pk_fma_f32 v[18:19], v[42:43], v[104:105], v[18:19] op_sel_hi:[1,0,1]
	v_pk_fma_f32 v[14:15], v[38:39], v[40:41], v[14:15] op_sel_hi:[1,0,1]
	v_pk_fma_f32 v[12:13], v[36:37], v[40:41], v[12:13] op_sel_hi:[1,0,1]
	v_mov_b32_e32 v40, v105
	v_pk_fma_f32 v[18:19], v[38:39], v[40:41], v[18:19] op_sel_hi:[1,0,1]
	v_pk_fma_f32 v[16:17], v[36:37], v[40:41], v[16:17] op_sel_hi:[1,0,1]
	ds_read2st64_b32 v[36:37], v69 offset0:4 offset1:5
	ds_read2st64_b32 v[38:39], v69 offset0:36 offset1:37
	ds_read2st64_b32 v[40:41], v69 offset0:68 offset1:69
	ds_read2st64_b32 v[42:43], v69 offset0:100 offset1:101
	ds_read2st64_b32 v[96:97], v69 offset0:132 offset1:133
	s_waitcnt vmcnt(3) lgkmcnt(4)
	v_pk_fma_f32 v[2:3], v[34:35], v[36:37], v[2:3] op_sel_hi:[1,0,1]
	v_pk_fma_f32 v[0:1], v[32:33], v[36:37], v[0:1] op_sel_hi:[1,0,1]
	s_waitcnt lgkmcnt(3)
	v_pk_fma_f32 v[4:5], v[32:33], v[38:39], v[4:5] op_sel_hi:[1,0,1]
	s_waitcnt lgkmcnt(2)
	v_pk_fma_f32 v[8:9], v[32:33], v[40:41], v[8:9] op_sel_hi:[1,0,1]
	s_waitcnt lgkmcnt(1)
	v_pk_fma_f32 v[12:13], v[32:33], v[42:43], v[12:13] op_sel_hi:[1,0,1]
	s_waitcnt lgkmcnt(0)
	v_pk_fma_f32 v[16:17], v[32:33], v[96:97], v[16:17] op_sel_hi:[1,0,1]
	v_mov_b32_e32 v32, v37
	v_pk_fma_f32 v[6:7], v[34:35], v[38:39], v[6:7] op_sel_hi:[1,0,1]
	s_waitcnt vmcnt(2)
	v_pk_fma_f32 v[2:3], v[30:31], v[32:33], v[2:3] op_sel_hi:[1,0,1]
	v_pk_fma_f32 v[0:1], v[28:29], v[32:33], v[0:1] op_sel_hi:[1,0,1]
	v_mov_b32_e32 v32, v39
	v_pk_fma_f32 v[10:11], v[34:35], v[40:41], v[10:11] op_sel_hi:[1,0,1]
	v_pk_fma_f32 v[6:7], v[30:31], v[32:33], v[6:7] op_sel_hi:[1,0,1]
	v_pk_fma_f32 v[4:5], v[28:29], v[32:33], v[4:5] op_sel_hi:[1,0,1]
	v_mov_b32_e32 v32, v41
	v_pk_fma_f32 v[14:15], v[34:35], v[42:43], v[14:15] op_sel_hi:[1,0,1]
	v_pk_fma_f32 v[10:11], v[30:31], v[32:33], v[10:11] op_sel_hi:[1,0,1]
	v_pk_fma_f32 v[8:9], v[28:29], v[32:33], v[8:9] op_sel_hi:[1,0,1]
	v_mov_b32_e32 v32, v43
	v_pk_fma_f32 v[18:19], v[34:35], v[96:97], v[18:19] op_sel_hi:[1,0,1]
	v_pk_fma_f32 v[14:15], v[30:31], v[32:33], v[14:15] op_sel_hi:[1,0,1]
	v_pk_fma_f32 v[12:13], v[28:29], v[32:33], v[12:13] op_sel_hi:[1,0,1]
	v_mov_b32_e32 v32, v97
	v_pk_fma_f32 v[18:19], v[30:31], v[32:33], v[18:19] op_sel_hi:[1,0,1]
	v_pk_fma_f32 v[16:17], v[28:29], v[32:33], v[16:17] op_sel_hi:[1,0,1]
	ds_read2st64_b32 v[28:29], v69 offset0:6 offset1:7
	ds_read2st64_b32 v[30:31], v69 offset0:38 offset1:39
	ds_read2st64_b32 v[32:33], v69 offset0:70 offset1:71
	ds_read2st64_b32 v[34:35], v69 offset0:102 offset1:103
	ds_read2st64_b32 v[36:37], v69 offset0:134 offset1:135
	s_waitcnt vmcnt(1) lgkmcnt(4)
	v_pk_fma_f32 v[2:3], v[26:27], v[28:29], v[2:3] op_sel_hi:[1,0,1]
	v_pk_fma_f32 v[0:1], v[24:25], v[28:29], v[0:1] op_sel_hi:[1,0,1]
	s_waitcnt lgkmcnt(3)
	v_pk_fma_f32 v[4:5], v[24:25], v[30:31], v[4:5] op_sel_hi:[1,0,1]
	s_waitcnt lgkmcnt(2)
	v_pk_fma_f32 v[8:9], v[24:25], v[32:33], v[8:9] op_sel_hi:[1,0,1]
	s_waitcnt lgkmcnt(1)
	v_pk_fma_f32 v[12:13], v[24:25], v[34:35], v[12:13] op_sel_hi:[1,0,1]
	s_waitcnt lgkmcnt(0)
	v_pk_fma_f32 v[16:17], v[24:25], v[36:37], v[16:17] op_sel_hi:[1,0,1]
	v_mov_b32_e32 v24, v29
	v_pk_fma_f32 v[6:7], v[26:27], v[30:31], v[6:7] op_sel_hi:[1,0,1]
	s_waitcnt vmcnt(0)
	v_pk_fma_f32 v[2:3], v[22:23], v[24:25], v[2:3] op_sel_hi:[1,0,1]
	v_pk_fma_f32 v[0:1], v[20:21], v[24:25], v[0:1] op_sel_hi:[1,0,1]
	v_mov_b32_e32 v24, v31
	v_pk_fma_f32 v[10:11], v[26:27], v[32:33], v[10:11] op_sel_hi:[1,0,1]
	v_pk_fma_f32 v[6:7], v[22:23], v[24:25], v[6:7] op_sel_hi:[1,0,1]
	v_pk_fma_f32 v[4:5], v[20:21], v[24:25], v[4:5] op_sel_hi:[1,0,1]
	v_mov_b32_e32 v24, v33
	v_pk_fma_f32 v[14:15], v[26:27], v[34:35], v[14:15] op_sel_hi:[1,0,1]
	v_pk_fma_f32 v[10:11], v[22:23], v[24:25], v[10:11] op_sel_hi:[1,0,1]
	v_pk_fma_f32 v[8:9], v[20:21], v[24:25], v[8:9] op_sel_hi:[1,0,1]
	v_mov_b32_e32 v24, v35
	v_pk_fma_f32 v[18:19], v[26:27], v[36:37], v[18:19] op_sel_hi:[1,0,1]
	v_pk_fma_f32 v[14:15], v[22:23], v[24:25], v[14:15] op_sel_hi:[1,0,1]
	v_pk_fma_f32 v[12:13], v[20:21], v[24:25], v[12:13] op_sel_hi:[1,0,1]
	v_mov_b32_e32 v24, v37
	v_pk_fma_f32 v[18:19], v[22:23], v[24:25], v[18:19] op_sel_hi:[1,0,1]
	v_pk_fma_f32 v[16:17], v[20:21], v[24:25], v[16:17] op_sel_hi:[1,0,1]
	v_add_u32_e32 v69, 0x800, v69
	s_cbranch_scc0 .LBB0_645
	ds_write_b128 v95, v[0:3] offset:40960
	ds_write_b128 v95, v[4:7] offset:40976
	ds_write_b128 v95, v[8:11] offset:40992
	ds_write_b128 v95, v[12:15] offset:41008
	ds_write_b128 v95, v[16:19] offset:41024
	s_waitcnt lgkmcnt(0)
	s_barrier
	s_and_saveexec_b64 s[2:3], s[52:53]
	s_cbranch_execz .LBB0_554
	ds_read2_b32 v[0:1], v93 offset1:160
	v_add_u32_e32 v2, 0xa400, v92
	ds_read2_b32 v[2:3], v2 offset0:64 offset1:224
	v_add_u32_e32 v4, 0xaa00, v92
	ds_read2_b32 v[4:5], v4 offset1:160
	s_waitcnt lgkmcnt(2)
	v_add_f32_e32 v0, 0, v0
	v_add_f32_e32 v0, v0, v1
	s_waitcnt lgkmcnt(1)
	v_add_f32_e32 v0, v0, v2
	v_add_f32_e32 v0, v0, v3
	s_waitcnt lgkmcnt(0)
	v_add_f32_e32 v0, v0, v4
	v_add_f32_e32 v6, v0, v5
	v_add_u32_e32 v0, 0xae00, v92
	ds_read2_b32 v[0:1], v0 offset0:64 offset1:224
	v_add_u32_e32 v2, 0xb400, v92
	ds_read2_b32 v[2:3], v2 offset1:160
	v_add_u32_e32 v4, 0xb800, v92
	ds_read2_b32 v[4:5], v4 offset0:64 offset1:224
	s_waitcnt lgkmcnt(2)
	v_add_f32_e32 v0, v6, v0
	v_add_f32_e32 v0, v0, v1
	s_waitcnt lgkmcnt(1)
	v_add_f32_e32 v0, v0, v2
	v_add_f32_e32 v0, v0, v3
	s_waitcnt lgkmcnt(0)
	v_add_f32_e32 v0, v0, v4
	v_add_f32_e32 v6, v0, v5
	v_add_u32_e32 v0, 0xbe00, v92
	ds_read2_b32 v[0:1], v0 offset1:160
	v_add_u32_e32 v2, 0xc200, v92
	ds_read2_b32 v[2:3], v2 offset0:64 offset1:224
	v_add_u32_e32 v4, 0xc800, v92
	ds_read2_b32 v[4:5], v4 offset1:160
	s_waitcnt lgkmcnt(2)
	v_add_f32_e32 v0, v6, v0
	v_add_f32_e32 v0, v0, v1
	s_waitcnt lgkmcnt(1)
	v_add_f32_e32 v0, v0, v2
	v_add_f32_e32 v0, v0, v3
	s_waitcnt lgkmcnt(0)
	v_add_f32_e32 v0, v0, v4
	v_add_f32_e32 v6, v0, v5
	v_add_u32_e32 v0, 0xcc00, v92
	ds_read2_b32 v[0:1], v0 offset0:64 offset1:224
	v_add_u32_e32 v2, 0xd200, v92
	ds_read2_b32 v[2:3], v2 offset1:160
	s_mul_i32 s5, s4, 0x3000
	v_readlane_b32 s80, v254, 18
	s_waitcnt lgkmcnt(1)
	v_add_f32_e32 v0, v6, v0
	v_add_f32_e32 v0, v0, v1
	s_waitcnt lgkmcnt(0)
	v_add_f32_e32 v0, v0, v2
	v_add_u32_e32 v2, s12, v90
	v_add_u32_e32 v6, s5, v2
	v_ashrrev_i32_e32 v7, 31, v6
	v_readlane_b32 s90, v254, 28
	v_readlane_b32 s91, v254, 29
	v_add_u32_e32 v4, 0xd600, v92
	ds_read2_b32 v[4:5], v4 offset0:64 offset1:224
	v_lshl_add_u64 v[6:7], v[6:7], 2, s[90:91]
	global_load_dword v8, v[6:7], off
	v_add_f32_e32 v0, v0, v3
	v_readlane_b32 s81, v254, 19
	s_waitcnt lgkmcnt(0)
	v_add_f32_e32 v3, v0, v4
	v_add_u32_e32 v0, 0xdc00, v92
	ds_read2_b32 v[0:1], v0 offset1:160
	v_add_f32_e32 v3, v3, v5
	v_add_u32_e32 v4, 0xe000, v92
	ds_read2_b32 v[4:5], v4 offset0:64 offset1:224
	v_readlane_b32 s82, v254, 20
	s_waitcnt lgkmcnt(1)
	v_add_f32_e32 v0, v3, v0
	v_add_f32_e32 v3, v0, v1
	v_add_u32_e32 v0, 0xe600, v92
	ds_read2_b32 v[0:1], v0 offset1:160
	s_waitcnt lgkmcnt(1)
	v_add_f32_e32 v3, v3, v4
	v_add_f32_e32 v3, v3, v5
	v_add_u32_e32 v4, 0xea00, v92
	ds_read2_b32 v[4:5], v4 offset0:64 offset1:224
	s_waitcnt lgkmcnt(1)
	v_add_f32_e32 v0, v3, v0
	v_add_f32_e32 v3, v0, v1
	v_add_u32_e32 v0, 0xf000, v92
	ds_read2_b32 v[0:1], v0 offset1:160
	s_waitcnt lgkmcnt(1)
	v_add_f32_e32 v3, v3, v4
	v_add_u32_e32 v4, 0xf400, v92
	v_add_f32_e32 v3, v3, v5
	ds_read2_b32 v[4:5], v4 offset0:64 offset1:224
	s_waitcnt lgkmcnt(1)
	v_add_f32_e32 v0, v3, v0
	v_add_u32_e32 v3, 0xfa00, v92
	ds_read2_b32 v[6:7], v3 offset1:160
	v_add_f32_e32 v0, v0, v1
	ds_read_b32 v1, v92 offset:65280
	ds_read_b32 v3, v93 offset:40320
	s_waitcnt lgkmcnt(3)
	v_add_f32_e32 v0, v0, v4
	v_add_f32_e32 v0, v0, v5
	s_waitcnt lgkmcnt(2)
	v_add_f32_e32 v0, v0, v6
	v_add_f32_e32 v0, v0, v7
	s_waitcnt lgkmcnt(1)
	v_add_f32_e32 v9, v0, v1
	v_add_u32_e32 v0, 0x6100, v93
	ds_read2_b32 v[0:1], v0 offset0:32 offset1:192
	v_add_u32_e32 v4, 0x6600, v93
	ds_read2_b32 v[4:5], v4 offset0:32 offset1:192
	v_add_u32_e32 v6, 0x6b00, v93
	ds_read2_b32 v[6:7], v6 offset0:32 offset1:192
	s_waitcnt lgkmcnt(2)
	v_add_f32_e32 v0, v9, v0
	v_add_f32_e32 v0, v0, v1
	s_waitcnt lgkmcnt(1)
	v_add_f32_e32 v0, v0, v4
	v_add_f32_e32 v0, v0, v5
	s_waitcnt lgkmcnt(0)
	v_add_f32_e32 v0, v0, v6
	v_add_f32_e32 v9, v0, v7
	v_add_u32_e32 v0, 0x7000, v93
	ds_read2_b32 v[0:1], v0 offset0:32 offset1:192
	v_add_u32_e32 v4, 0x7500, v93
	ds_read2_b32 v[4:5], v4 offset0:32 offset1:192
	v_add_u32_e32 v6, 0x7a00, v93
	ds_read2_b32 v[6:7], v6 offset0:32 offset1:192
	s_waitcnt lgkmcnt(2)
	v_add_f32_e32 v0, v9, v0
	v_add_f32_e32 v0, v0, v1
	s_waitcnt lgkmcnt(1)
	v_add_f32_e32 v0, v0, v4
	v_add_f32_e32 v0, v0, v5
	s_waitcnt lgkmcnt(0)
	v_add_f32_e32 v0, v0, v6
	v_add_f32_e32 v9, v0, v7
	v_add_u32_e32 v0, 0x7f00, v93
	ds_read2_b32 v[0:1], v0 offset0:32 offset1:192
	v_add_u32_e32 v4, 0x8400, v93
	ds_read2_b32 v[4:5], v4 offset0:32 offset1:192
	v_add_u32_e32 v6, 0x8900, v93
	ds_read2_b32 v[6:7], v6 offset0:32 offset1:192
	s_waitcnt lgkmcnt(2)
	v_add_f32_e32 v0, v9, v0
	v_add_f32_e32 v0, v0, v1
	s_waitcnt lgkmcnt(1)
	v_add_f32_e32 v0, v0, v4
	v_add_f32_e32 v0, v0, v5
	s_waitcnt lgkmcnt(0)
	v_add_f32_e32 v0, v0, v6
	v_add_f32_e32 v9, v0, v7
	v_add_u32_e32 v0, 0x8e00, v93
	ds_read2_b32 v[0:1], v0 offset0:32 offset1:192
	v_add_u32_e32 v4, 0x9300, v93
	ds_read2_b32 v[4:5], v4 offset0:32 offset1:192
	v_add_u32_e32 v6, 0x9800, v93
	ds_read2_b32 v[6:7], v6 offset0:32 offset1:192
	s_waitcnt lgkmcnt(2)
	v_add_f32_e32 v0, v9, v0
	v_add_f32_e32 v0, v0, v1
	s_waitcnt lgkmcnt(1)
	v_add_f32_e32 v0, v0, v4
	v_add_f32_e32 v0, v0, v5
	s_waitcnt lgkmcnt(0)
	v_add_f32_e32 v0, v0, v6
	v_add_f32_e32 v0, v0, v7
	v_add_f32_e32 v0, v0, v3
	s_waitcnt vmcnt(0)
	v_add_f32_e32 v6, v0, v8
	v_mad_u64_u32 v[0:1], s[4:5], s4, 5, v[56:57]
	v_readlane_b32 s4, v254, 53
	v_readlane_b32 s5, v254, 54
	v_ashrrev_i32_e32 v3, 31, v2
	v_readlane_b32 s83, v254, 21
	v_mov_b64_e32 v[4:5], s[4:5]
	v_mad_i64_i32 v[0:1], s[4:5], v0, s9, v[4:5]
	v_lshl_add_u64 v[0:1], v[2:3], 2, v[0:1]
	v_readlane_b32 s84, v254, 22
	v_readlane_b32 s85, v254, 23
	v_readlane_b32 s86, v254, 24
	v_readlane_b32 s87, v254, 25
	v_readlane_b32 s88, v254, 26
	v_readlane_b32 s89, v254, 27
	v_readlane_b32 s92, v254, 30
	v_readlane_b32 s93, v254, 31
	v_readlane_b32 s94, v254, 32
	v_readlane_b32 s95, v254, 33
	global_store_dword v[0:1], v6, off
	s_branch .LBB0_554

.LBB0_649:
	v_mov_b32_e32 v2, v224
	v_readlane_b32 s2, v252, 52
	v_lshlrev_b32_e32 v0, 4, v2
	s_and_b32 s0, s11, 0xffffff00
	s_and_b32 s1, s10, 0xfc0
	v_and_b32_e32 v192, 0xf0, v0
	v_readlane_b32 s3, v252, 53
	v_ashrrev_i32_e32 v3, 4, v2
	v_add_u32_e32 v8, 0x200, v2
	s_add_i32 s4, s1, 0x200
	v_lshl_add_u64 v[0:1], s[2:3], 0, v[192:193]
	v_add_u32_e32 v4, s0, v3
	s_movk_i32 s5, 0x4800
	v_ashrrev_i32_e32 v38, 4, v8
	v_add_u32_e32 v12, 0x400, v2
	v_mad_i64_i32 v[4:5], s[2:3], v4, s5, v[0:1]
	s_lshl_b32 s64, s4, 2
	v_add_u32_e32 v8, s0, v38
	v_ashrrev_i32_e32 v39, 4, v12
	v_add_u32_e32 v16, 0x600, v2
	v_lshl_add_u64 v[4:5], v[4:5], 0, s[64:65]
	v_mad_i64_i32 v[8:9], s[2:3], v8, s5, v[0:1]
	v_add_u32_e32 v12, s0, v39
	v_ashrrev_i32_e32 v40, 4, v16
	v_add_u32_e32 v20, 0x800, v2
	global_load_dwordx4 v[4:7], v[4:5], off nt
	v_lshl_add_u64 v[8:9], v[8:9], 0, s[64:65]
	v_mad_i64_i32 v[12:13], s[2:3], v12, s5, v[0:1]
	v_add_u32_e32 v16, s0, v40
	v_ashrrev_i32_e32 v41, 4, v20
	v_add_u32_e32 v24, 0xa00, v2
	global_load_dwordx4 v[8:11], v[8:9], off nt
	v_lshl_add_u64 v[12:13], v[12:13], 0, s[64:65]
	v_mad_i64_i32 v[16:17], s[2:3], v16, s5, v[0:1]
	v_add_u32_e32 v20, s0, v41
	v_ashrrev_i32_e32 v42, 4, v24
	global_load_dwordx4 v[12:15], v[12:13], off nt
	v_lshl_add_u64 v[16:17], v[16:17], 0, s[64:65]
	v_mad_i64_i32 v[20:21], s[2:3], v20, s5, v[0:1]
	v_add_u32_e32 v24, s0, v42
	global_load_dwordx4 v[16:19], v[16:17], off nt
	v_lshl_add_u64 v[20:21], v[20:21], 0, s[64:65]
	v_mad_i64_i32 v[24:25], s[2:3], v24, s5, v[0:1]
	v_add_u32_e32 v28, 0xc00, v2
	v_add_u32_e32 v32, 0xe00, v2
	global_load_dwordx4 v[20:23], v[20:21], off nt
	v_lshl_add_u64 v[24:25], v[24:25], 0, s[64:65]
	v_ashrrev_i32_e32 v43, 4, v28
	v_ashrrev_i32_e32 v44, 4, v32
	global_load_dwordx4 v[24:27], v[24:25], off nt
	v_add_u32_e32 v28, s0, v43
	v_add_u32_e32 v32, s0, v44
	v_mad_i64_i32 v[28:29], s[2:3], v28, s5, v[0:1]
	v_mad_i64_i32 v[0:1], s[2:3], v32, s5, v[0:1]
	v_lshl_add_u64 v[28:29], v[28:29], 0, s[64:65]
	v_lshl_add_u64 v[0:1], v[0:1], 0, s[64:65]
	global_load_dwordx4 v[28:31], v[28:29], off nt
	s_nop 0
	global_load_dwordx4 v[32:35], v[0:1], off nt
	v_add_u32_e32 v0, 0, v192
	v_mad_u64_u32 v[36:37], s[2:3], v3, s97, v[0:1]
	v_ashrrev_i32_e32 v3, 3, v2
	s_waitcnt vmcnt(0)
	ds_write2_b32 v36, v4, v5 offset1:1
	ds_write2_b32 v36, v6, v7 offset0:2 offset1:3
	v_mad_u64_u32 v[4:5], s[2:3], v38, s97, v[0:1]
	ds_write2_b32 v4, v8, v9 offset1:1
	ds_write2_b32 v4, v10, v11 offset0:2 offset1:3
	v_mad_u64_u32 v[4:5], s[2:3], v39, s97, v[0:1]
	ds_write2_b32 v4, v12, v13 offset1:1
	ds_write2_b32 v4, v14, v15 offset0:2 offset1:3
	v_mad_u64_u32 v[4:5], s[2:3], v40, s97, v[0:1]
	ds_write2_b32 v4, v16, v17 offset1:1
	ds_write2_b32 v4, v18, v19 offset0:2 offset1:3
	v_mad_u64_u32 v[4:5], s[2:3], v41, s97, v[0:1]
	ds_write2_b32 v4, v20, v21 offset1:1
	ds_write2_b32 v4, v22, v23 offset0:2 offset1:3
	v_mad_u64_u32 v[4:5], s[2:3], v42, s97, v[0:1]
	ds_write2_b32 v4, v24, v25 offset1:1
	ds_write2_b32 v4, v26, v27 offset0:2 offset1:3
	v_mad_u64_u32 v[4:5], s[2:3], v43, s97, v[0:1]
	v_mad_u64_u32 v[0:1], s[2:3], v44, s97, v[0:1]
	v_add_u32_e32 v1, s4, v3
	s_movk_i32 s2, 0x5ff
	v_cmp_lt_i32_e32 vcc, s2, v1
	ds_write2_b32 v4, v28, v29 offset1:1
	ds_write2_b32 v4, v30, v31 offset0:2 offset1:3
	ds_write2_b32 v0, v32, v33 offset1:1
	ds_write2_b32 v0, v34, v35 offset0:2 offset1:3
	s_waitcnt lgkmcnt(0)
	s_barrier
	s_and_saveexec_b64 s[2:3], vcc
	s_xor_b64 s[2:3], exec, s[2:3]
	s_cbranch_execz .LBB0_655
	s_movk_i32 s4, 0xdff
	v_cmp_lt_u32_e32 vcc, s4, v1
	s_and_saveexec_b64 s[4:5], vcc
	s_xor_b64 s[4:5], exec, s[4:5]
	v_add_u32_e32 v0, 0xfffff600, v1
	s_andn2_saveexec_b64 s[4:5], s[4:5]
	v_lshlrev_b32_e32 v0, 1, v1
	v_and_b32_e32 v0, 56, v0
	s_movk_i32 s9, 0xfc0
	v_and_or_b32 v0, v1, s9, v0
	v_lshrrev_b32_e32 v1, 3, v3
	v_and_b32_e32 v1, 4, v1
	v_bfe_u32 v4, v2, 3, 2
	v_or3_b32 v0, v0, v1, v4
	v_add_u32_e32 v0, 0x600, v0
	s_or_b64 exec, exec, s[4:5]
